# v52 plus removal of the 16 mid-block s_setprio 0/1 toggles inside the GEMM K-loop MFMA segments (32 MFMAs run as one chain)
# speedup vs baseline: 1.0135x; 1.0135x over previous
; #define PG8_STAGE(bufoff, gbase, voff) do { _Pragma("unroll") for (int _i = 0; _i < 2; ++_i) \
;         __builtin_amdgcn_global_load_lds((const unsigned*)((const char*)(gbase) + (voff)[_i]), (PG8_LAS unsigned*)(lds + (bufoff) + ldsw + _i * 8192), 16, 0, 0); } while (0)
; #define PG8_LDA(dst, b, h) do { _Pragma("unroll") for (int m = 0; m < 4; ++m) _Pragma("unroll") for (int k = 0; k < 2; ++k) dst[m][k] = *(const PG8_LAS bf16x8*)(lds + PG8_SA(b, h) + aoff + m * 2048 + k * 1024); } while (0)
; #define PG8_LDB(dst, b, h) do { _Pragma("unroll") for (int n = 0; n < 2; ++n) _Pragma("unroll") for (int k = 0; k < 2; ++k) dst[n][k] = *(const PG8_LAS bf16x8*)(lds + PG8_SB(b, h) + boff + n * 2048 + k * 1024); } while (0)
; #define PG8_MMA(ai, bj, At, Bt) do { __builtin_amdgcn_s_setprio(1); _Pragma("unroll") for (int m = 0; m < 4; ++m) _Pragma("unroll") for (int n = 0; n < 2; ++n) _Pragma("unroll") for (int k = 0; k < 2; ++k) \
;         acc[ai][bj][m][n] = __builtin_amdgcn_mfma_f32_16x16x32_bf16(Bt[n][k], At[m][k], acc[ai][bj][m][n], 0, 0, 0); __builtin_amdgcn_s_setprio(0); } while (0)
; #define PG8_WAIT_V(n) asm volatile("s_waitcnt vmcnt(" #n ")" ::: "memory")
; #define PG8_WAIT_L(n) asm volatile("s_waitcnt lgkmcnt(" #n ")" ::: "memory")
; template <class Epi, class Sched, bool ALIGN_EPI = false, bool SP2 = false>
; __device__ __forceinline__ void gemm_phase(PG8_LAS unsigned char* lds, const Gemm g, const Sched& S, const Epi& E) {
;     ...
;             const bool last = (t == unt - 2);
;             const char* a1 = cA + (size_t)(t + 1) * kstep;
;             const char* a2 = last ? nA : cA + (size_t)(t + 2) * kstep; const char* b2 = last ? nB : cB + (size_t)(t + 2) * kstep;
;             const char* a3 = a2 + kstep; const char* b3 = b2 + kstep;
;             if (last && has_next) S.a_ready(nxt);
;             if constexpr (SP2) {
;             PG8_LDB(B0, 0, 0); PG8_LDB(B1, 0, 1); PG8_SCHED; PG8_LDA(At, 0, 0); PG8_STAGE(PG8_SA(1, 1), a1 + hstep, voffA);
;             PG8_WAIT_V(8); PG8_WAIT_L(0); PG8_BAR; PG8_MMA(0, 0, At, B0); PG8_MMA(0, 1, At, B1); PG8_BAR; PG8_SCHED;
;             PG8_LDA(At, 0, 1); PG8_STAGE(PG8_SB(0, 0), b2, voffB); PG8_STAGE(PG8_SB(0, 1), b2 + hstep, voffB); PG8_STAGE(PG8_SA(0, 0), a2, voffA);
;             PG8_WAIT_V(8); PG8_WAIT_L(0); PG8_BAR; PG8_MMA(1, 0, At, B0); PG8_MMA(1, 1, At, B1); PG8_BAR; PG8_SCHED;
.LBB0_197:
	s_add_u32 s6, s46, 0xfffc0080
	s_addc_u32 s7, s47, -1
	s_add_i32 s71, 0, 0x10000
	s_cmp_eq_u32 s70, 12
	s_cselect_b32 s51, s35, s7
	s_cselect_b32 s50, s66, s6
	s_cselect_b32 s49, s31, s69
	s_cselect_b32 s48, s67, s68
	s_add_i32 s6, 0, 0x14000
	v_add_u32_e32 v156, s71, v145
	v_add_u32_e32 v172, s6, v145
	ds_read_b128 v[140:143], v156
	ds_read_b128 v[148:151], v156 offset:1024
	ds_read_b128 v[152:155], v156 offset:2048
	ds_read_b128 v[156:159], v156 offset:3072
	ds_read_b128 v[160:163], v172
	ds_read_b128 v[164:167], v172 offset:1024
	ds_read_b128 v[168:171], v172 offset:2048
	ds_read_b128 v[172:175], v172 offset:3072
	s_add_i32 m0, s45, 0xc000
	ds_read_b128 v[176:179], v147
	ds_read_b128 v[180:183], v147 offset:1024
	ds_read_b128 v[184:187], v147 offset:2048
	ds_read_b128 v[188:191], v147 offset:3072
	ds_read_b128 v[192:195], v147 offset:4096
	ds_read_b128 v[196:199], v147 offset:5120
	ds_read_b128 v[200:203], v147 offset:6144
	ds_read_b128 v[212:215], v147 offset:7168
	global_load_lds_dwordx4 v136, s[46:47]
	s_add_i32 m0, s45, 0xe000
	s_nop 0
	global_load_lds_dwordx4 v138, s[46:47]
	s_waitcnt vmcnt(8)
	s_waitcnt lgkmcnt(0)
	s_barrier
	s_setprio 1
	v_mfma_f32_16x16x32_bf16 v[126:129], v[140:143], v[176:179], v[126:129]
	v_mfma_f32_16x16x32_bf16 v[122:125], v[152:155], v[176:179], v[122:125]
	v_mfma_f32_16x16x32_bf16 v[118:121], v[140:143], v[184:187], v[118:121]
	v_mfma_f32_16x16x32_bf16 v[110:113], v[152:155], v[184:187], v[110:113]
	v_mfma_f32_16x16x32_bf16 v[102:105], v[140:143], v[192:195], v[102:105]
	v_mfma_f32_16x16x32_bf16 v[94:97], v[152:155], v[192:195], v[94:97]
	v_mfma_f32_16x16x32_bf16 v[86:89], v[140:143], v[200:203], v[86:89]
	v_mfma_f32_16x16x32_bf16 v[78:81], v[152:155], v[200:203], v[78:81]
	v_mfma_f32_16x16x32_bf16 v[126:129], v[148:151], v[180:183], v[126:129]
	v_mfma_f32_16x16x32_bf16 v[122:125], v[156:159], v[180:183], v[122:125]
	v_mfma_f32_16x16x32_bf16 v[118:121], v[148:151], v[188:191], v[118:121]
	v_mfma_f32_16x16x32_bf16 v[110:113], v[156:159], v[188:191], v[110:113]
	v_mfma_f32_16x16x32_bf16 v[102:105], v[148:151], v[196:199], v[102:105]
	v_mfma_f32_16x16x32_bf16 v[94:97], v[156:159], v[196:199], v[94:97]
	v_mfma_f32_16x16x32_bf16 v[86:89], v[148:151], v[212:215], v[86:89]
	v_mfma_f32_16x16x32_bf16 v[78:81], v[156:159], v[212:215], v[78:81]
	v_mfma_f32_16x16x32_bf16 v[114:117], v[160:163], v[176:179], v[114:117]
	v_mfma_f32_16x16x32_bf16 v[106:109], v[168:171], v[176:179], v[106:109]
	v_mfma_f32_16x16x32_bf16 v[98:101], v[160:163], v[184:187], v[98:101]
	v_mfma_f32_16x16x32_bf16 v[90:93], v[168:171], v[184:187], v[90:93]
	v_mfma_f32_16x16x32_bf16 v[82:85], v[160:163], v[192:195], v[82:85]
	v_mfma_f32_16x16x32_bf16 v[74:77], v[168:171], v[192:195], v[74:77]
	v_mfma_f32_16x16x32_bf16 v[70:73], v[160:163], v[200:203], v[70:73]
	v_mfma_f32_16x16x32_bf16 v[66:69], v[168:171], v[200:203], v[66:69]
	v_mfma_f32_16x16x32_bf16 v[114:117], v[164:167], v[180:183], v[114:117]
	v_mfma_f32_16x16x32_bf16 v[106:109], v[172:175], v[180:183], v[106:109]
	v_mfma_f32_16x16x32_bf16 v[98:101], v[164:167], v[188:191], v[98:101]
	v_mfma_f32_16x16x32_bf16 v[90:93], v[172:175], v[188:191], v[90:93]
	v_mfma_f32_16x16x32_bf16 v[82:85], v[164:167], v[196:199], v[82:85]
	v_mfma_f32_16x16x32_bf16 v[74:77], v[172:175], v[196:199], v[74:77]
	v_mfma_f32_16x16x32_bf16 v[70:73], v[164:167], v[212:215], v[70:73]
	v_mfma_f32_16x16x32_bf16 v[66:69], v[172:175], v[212:215], v[66:69]
	s_setprio 0
	s_barrier
	s_add_i32 s7, s71, s60
	s_add_u32 s98, s48, s22
	s_addc_u32 s99, s49, s23
	s_mov_b32 m0, s7
	ds_read_b128 v[176:179], v147 offset:16384
	ds_read_b128 v[180:183], v147 offset:17408
	ds_read_b128 v[184:187], v147 offset:18432
	ds_read_b128 v[188:191], v147 offset:19456
	ds_read_b128 v[192:195], v147 offset:20480
	ds_read_b128 v[196:199], v147 offset:21504
	ds_read_b128 v[200:203], v147 offset:22528
	ds_read_b128 v[212:215], v147 offset:23552
	global_load_lds_dwordx4 v0, s[48:49]
	s_add_i32 m0, s7, 0x2000
	s_add_u32 s76, s48, 0x40000
	s_addc_u32 s77, s49, 0
	s_add_i32 s6, s6, s60
	global_load_lds_dwordx4 v134, s[48:49]
	s_mov_b32 m0, s6
	s_add_u32 s100, s50, s22
	s_addc_u32 s101, s51, s23
	global_load_lds_dwordx4 v0, s[76:77]
	s_add_i32 m0, s6, 0x2000
	s_nop 0
	global_load_lds_dwordx4 v134, s[76:77]
	s_mov_b32 m0, s45
	s_nop 0
	global_load_lds_dwordx4 v130, s[50:51]
	s_mov_b32 m0, s4
	s_nop 0
	global_load_lds_dwordx4 v132, s[50:51]
	s_waitcnt vmcnt(8)
	s_waitcnt lgkmcnt(0)
	s_barrier
	s_setprio 1
	v_mfma_f32_16x16x32_bf16 v[62:65], v[140:143], v[176:179], v[62:65]
	v_mfma_f32_16x16x32_bf16 v[58:61], v[152:155], v[176:179], v[58:61]
	v_mfma_f32_16x16x32_bf16 v[54:57], v[140:143], v[184:187], v[54:57]
	v_mfma_f32_16x16x32_bf16 v[46:49], v[152:155], v[184:187], v[46:49]
	v_mfma_f32_16x16x32_bf16 v[38:41], v[140:143], v[192:195], v[38:41]
	v_mfma_f32_16x16x32_bf16 v[30:33], v[152:155], v[192:195], v[30:33]
	v_mfma_f32_16x16x32_bf16 v[22:25], v[140:143], v[200:203], v[22:25]
	v_mfma_f32_16x16x32_bf16 v[14:17], v[152:155], v[200:203], v[14:17]
	v_mfma_f32_16x16x32_bf16 v[62:65], v[148:151], v[180:183], v[62:65]
	v_mfma_f32_16x16x32_bf16 v[58:61], v[156:159], v[180:183], v[58:61]
	v_mfma_f32_16x16x32_bf16 v[54:57], v[148:151], v[188:191], v[54:57]
	v_mfma_f32_16x16x32_bf16 v[46:49], v[156:159], v[188:191], v[46:49]
	v_mfma_f32_16x16x32_bf16 v[38:41], v[148:151], v[196:199], v[38:41]
	v_mfma_f32_16x16x32_bf16 v[30:33], v[156:159], v[196:199], v[30:33]
	v_mfma_f32_16x16x32_bf16 v[22:25], v[148:151], v[212:215], v[22:25]
	v_mfma_f32_16x16x32_bf16 v[14:17], v[156:159], v[212:215], v[14:17]
	v_mfma_f32_16x16x32_bf16 v[50:53], v[160:163], v[176:179], v[50:53]
	v_mfma_f32_16x16x32_bf16 v[42:45], v[168:171], v[176:179], v[42:45]
	v_mfma_f32_16x16x32_bf16 v[34:37], v[160:163], v[184:187], v[34:37]
	v_mfma_f32_16x16x32_bf16 v[26:29], v[168:171], v[184:187], v[26:29]
	v_mfma_f32_16x16x32_bf16 v[18:21], v[160:163], v[192:195], v[18:21]
	v_mfma_f32_16x16x32_bf16 v[10:13], v[168:171], v[192:195], v[10:13]
	v_mfma_f32_16x16x32_bf16 v[6:9], v[160:163], v[200:203], v[6:9]
	v_mfma_f32_16x16x32_bf16 v[2:5], v[168:171], v[200:203], v[2:5]
	v_mfma_f32_16x16x32_bf16 v[50:53], v[164:167], v[180:183], v[50:53]
	v_mfma_f32_16x16x32_bf16 v[42:45], v[172:175], v[180:183], v[42:45]
	v_mfma_f32_16x16x32_bf16 v[34:37], v[164:167], v[188:191], v[34:37]
	v_mfma_f32_16x16x32_bf16 v[26:29], v[172:175], v[188:191], v[26:29]
	v_mfma_f32_16x16x32_bf16 v[18:21], v[164:167], v[196:199], v[18:21]
	v_mfma_f32_16x16x32_bf16 v[10:13], v[172:175], v[196:199], v[10:13]
	v_mfma_f32_16x16x32_bf16 v[6:9], v[164:167], v[212:215], v[6:9]
	v_mfma_f32_16x16x32_bf16 v[2:5], v[172:175], v[212:215], v[2:5]
	s_setprio 0
	s_barrier
; #define PG8_STAGE(bufoff, gbase, voff) do { _Pragma("unroll") for (int _i = 0; _i < 2; ++_i) \
;         __builtin_amdgcn_global_load_lds((const unsigned*)((const char*)(gbase) + (voff)[_i]), (PG8_LAS unsigned*)(lds + (bufoff) + ldsw + _i * 8192), 16, 0, 0); } while (0)
; #define PG8_LDA(dst, b, h) do { _Pragma("unroll") for (int m = 0; m < 4; ++m) _Pragma("unroll") for (int k = 0; k < 2; ++k) dst[m][k] = *(const PG8_LAS bf16x8*)(lds + PG8_SA(b, h) + aoff + m * 2048 + k * 1024); } while (0)
; #define PG8_LDB(dst, b, h) do { _Pragma("unroll") for (int n = 0; n < 2; ++n) _Pragma("unroll") for (int k = 0; k < 2; ++k) dst[n][k] = *(const PG8_LAS bf16x8*)(lds + PG8_SB(b, h) + boff + n * 2048 + k * 1024); } while (0)
; #define PG8_MMA(ai, bj, At, Bt) do { __builtin_amdgcn_s_setprio(1); _Pragma("unroll") for (int m = 0; m < 4; ++m) _Pragma("unroll") for (int n = 0; n < 2; ++n) _Pragma("unroll") for (int k = 0; k < 2; ++k) \
;         acc[ai][bj][m][n] = __builtin_amdgcn_mfma_f32_16x16x32_bf16(Bt[n][k], At[m][k], acc[ai][bj][m][n], 0, 0, 0); __builtin_amdgcn_s_setprio(0); } while (0)
; #define PG8_WAIT_V(n) asm volatile("s_waitcnt vmcnt(" #n ")" ::: "memory")
; #define PG8_WAIT_L(n) asm volatile("s_waitcnt lgkmcnt(" #n ")" ::: "memory")
; #define PG8_BAR __builtin_amdgcn_s_barrier()
; #define PG8_SCHED __builtin_amdgcn_sched_barrier(0)
; template <class Epi, class Sched, bool ALIGN_EPI = false, bool SP2 = false>
; __device__ __forceinline__ void gemm_phase(PG8_LAS unsigned char* lds, const Gemm g, const Sched& S, const Epi& E) {
;     ...
;             PG8_LDB(B0, 1, 0); PG8_LDB(B1, 1, 1); PG8_SCHED; PG8_LDA(At, 1, 0); PG8_STAGE(PG8_SA(0, 1), a2 + hstep, voffA);
;             PG8_WAIT_V(8); PG8_WAIT_L(0); PG8_BAR; PG8_MMA(0, 0, At, B0); PG8_MMA(0, 1, At, B1); PG8_BAR; PG8_SCHED;
;             PG8_LDA(At, 1, 1); PG8_STAGE(PG8_SB(1, 0), b3, voffB); PG8_STAGE(PG8_SB(1, 1), b3 + hstep, voffB); PG8_STAGE(PG8_SA(1, 0), a3, voffA);
;             PG8_WAIT_V(8); PG8_WAIT_L(0); PG8_BAR; PG8_MMA(1, 0, At, B0); PG8_MMA(1, 1, At, B1); PG8_BAR; PG8_SCHED;
;     ...
;         if constexpr (ALIGN_EPI) { if (wr == 0) PG8_BAR; }
	s_add_i32 s6, 0, 0x18000
	s_add_i32 s7, 0, 0x1c000
	v_add_u32_e32 v156, s6, v145
	v_add_u32_e32 v172, s7, v145
	ds_read_b128 v[140:143], v156
	ds_read_b128 v[148:151], v156 offset:1024
	ds_read_b128 v[152:155], v156 offset:2048
	ds_read_b128 v[156:159], v156 offset:3072
	ds_read_b128 v[160:163], v172
	ds_read_b128 v[164:167], v172 offset:1024
	ds_read_b128 v[168:171], v172 offset:2048
	ds_read_b128 v[172:175], v172 offset:3072
	s_add_u32 s50, s50, 0x40000
	s_addc_u32 s51, s51, 0
	s_mov_b32 m0, s5
	ds_read_b128 v[176:179], v147 offset:32768
	ds_read_b128 v[180:183], v147 offset:33792
	ds_read_b128 v[184:187], v147 offset:34816
	ds_read_b128 v[188:191], v147 offset:35840
	ds_read_b128 v[192:195], v147 offset:36864
	ds_read_b128 v[196:199], v147 offset:37888
	ds_read_b128 v[200:203], v147 offset:38912
	ds_read_b128 v[212:215], v147 offset:39936
	global_load_lds_dwordx4 v130, s[50:51]
	s_mov_b32 m0, s61
	s_nop 0
	global_load_lds_dwordx4 v132, s[50:51]
	s_waitcnt vmcnt(8)
	s_waitcnt lgkmcnt(0)
	s_barrier
	s_setprio 1
	v_mfma_f32_16x16x32_bf16 v[126:129], v[140:143], v[176:179], v[126:129]
	v_mfma_f32_16x16x32_bf16 v[122:125], v[152:155], v[176:179], v[122:125]
	v_mfma_f32_16x16x32_bf16 v[118:121], v[140:143], v[184:187], v[118:121]
	v_mfma_f32_16x16x32_bf16 v[110:113], v[152:155], v[184:187], v[110:113]
	v_mfma_f32_16x16x32_bf16 v[102:105], v[140:143], v[192:195], v[102:105]
	v_mfma_f32_16x16x32_bf16 v[94:97], v[152:155], v[192:195], v[94:97]
	v_mfma_f32_16x16x32_bf16 v[86:89], v[140:143], v[200:203], v[86:89]
	v_mfma_f32_16x16x32_bf16 v[78:81], v[152:155], v[200:203], v[78:81]
	v_mfma_f32_16x16x32_bf16 v[126:129], v[148:151], v[180:183], v[126:129]
	v_mfma_f32_16x16x32_bf16 v[122:125], v[156:159], v[180:183], v[122:125]
	v_mfma_f32_16x16x32_bf16 v[118:121], v[148:151], v[188:191], v[118:121]
	v_mfma_f32_16x16x32_bf16 v[110:113], v[156:159], v[188:191], v[110:113]
	v_mfma_f32_16x16x32_bf16 v[102:105], v[148:151], v[196:199], v[102:105]
	v_mfma_f32_16x16x32_bf16 v[94:97], v[156:159], v[196:199], v[94:97]
	v_mfma_f32_16x16x32_bf16 v[86:89], v[148:151], v[212:215], v[86:89]
	v_mfma_f32_16x16x32_bf16 v[78:81], v[156:159], v[212:215], v[78:81]
	v_mfma_f32_16x16x32_bf16 v[114:117], v[160:163], v[176:179], v[114:117]
	v_mfma_f32_16x16x32_bf16 v[106:109], v[168:171], v[176:179], v[106:109]
	v_mfma_f32_16x16x32_bf16 v[98:101], v[160:163], v[184:187], v[98:101]
	v_mfma_f32_16x16x32_bf16 v[90:93], v[168:171], v[184:187], v[90:93]
	v_mfma_f32_16x16x32_bf16 v[82:85], v[160:163], v[192:195], v[82:85]
	v_mfma_f32_16x16x32_bf16 v[74:77], v[168:171], v[192:195], v[74:77]
	v_mfma_f32_16x16x32_bf16 v[70:73], v[160:163], v[200:203], v[70:73]
	v_mfma_f32_16x16x32_bf16 v[66:69], v[168:171], v[200:203], v[66:69]
	v_mfma_f32_16x16x32_bf16 v[114:117], v[164:167], v[180:183], v[114:117]
	v_mfma_f32_16x16x32_bf16 v[106:109], v[172:175], v[180:183], v[106:109]
	v_mfma_f32_16x16x32_bf16 v[98:101], v[164:167], v[188:191], v[98:101]
	v_mfma_f32_16x16x32_bf16 v[90:93], v[172:175], v[188:191], v[90:93]
	v_mfma_f32_16x16x32_bf16 v[82:85], v[164:167], v[196:199], v[82:85]
	v_mfma_f32_16x16x32_bf16 v[74:77], v[172:175], v[196:199], v[74:77]
	v_mfma_f32_16x16x32_bf16 v[70:73], v[164:167], v[212:215], v[70:73]
	v_mfma_f32_16x16x32_bf16 v[66:69], v[172:175], v[212:215], v[66:69]
	s_setprio 0
	s_barrier
	s_add_i32 s6, s6, s60
	s_mov_b32 m0, s6
	ds_read_b128 v[176:179], v147 offset:49152
	ds_read_b128 v[180:183], v147 offset:50176
	ds_read_b128 v[184:187], v147 offset:51200
	ds_read_b128 v[188:191], v147 offset:52224
	ds_read_b128 v[192:195], v147 offset:53248
	ds_read_b128 v[196:199], v147 offset:54272
	ds_read_b128 v[200:203], v147 offset:55296
	ds_read_b128 v[212:215], v147 offset:56320
	global_load_lds_dwordx4 v0, s[98:99]
	s_add_i32 m0, s6, 0x2000
	s_add_u32 s48, s48, 0x40080
	s_addc_u32 s49, s49, 0
	s_add_i32 s6, s7, s60
	global_load_lds_dwordx4 v134, s[98:99]
	s_mov_b32 m0, s6
	s_nop 0
	global_load_lds_dwordx4 v0, s[48:49]
	s_add_i32 m0, s6, 0x2000
	s_nop 0
	global_load_lds_dwordx4 v134, s[48:49]
	s_mov_b32 m0, s62
	s_nop 0
	global_load_lds_dwordx4 v130, s[100:101]
	s_mov_b32 m0, s63
	s_nop 0
	global_load_lds_dwordx4 v132, s[100:101]
	s_waitcnt vmcnt(8)
	s_waitcnt lgkmcnt(0)
	s_barrier
	s_setprio 1
	v_mfma_f32_16x16x32_bf16 v[62:65], v[140:143], v[176:179], v[62:65]
	v_mfma_f32_16x16x32_bf16 v[58:61], v[152:155], v[176:179], v[58:61]
	v_mfma_f32_16x16x32_bf16 v[54:57], v[140:143], v[184:187], v[54:57]
	v_mfma_f32_16x16x32_bf16 v[46:49], v[152:155], v[184:187], v[46:49]
	v_mfma_f32_16x16x32_bf16 v[38:41], v[140:143], v[192:195], v[38:41]
	v_mfma_f32_16x16x32_bf16 v[30:33], v[152:155], v[192:195], v[30:33]
	v_mfma_f32_16x16x32_bf16 v[22:25], v[140:143], v[200:203], v[22:25]
	v_mfma_f32_16x16x32_bf16 v[14:17], v[152:155], v[200:203], v[14:17]
	v_mfma_f32_16x16x32_bf16 v[62:65], v[148:151], v[180:183], v[62:65]
	v_mfma_f32_16x16x32_bf16 v[58:61], v[156:159], v[180:183], v[58:61]
	v_mfma_f32_16x16x32_bf16 v[54:57], v[148:151], v[188:191], v[54:57]
	v_mfma_f32_16x16x32_bf16 v[46:49], v[156:159], v[188:191], v[46:49]
	v_mfma_f32_16x16x32_bf16 v[38:41], v[148:151], v[196:199], v[38:41]
	v_mfma_f32_16x16x32_bf16 v[30:33], v[156:159], v[196:199], v[30:33]
	v_mfma_f32_16x16x32_bf16 v[22:25], v[148:151], v[212:215], v[22:25]
	v_mfma_f32_16x16x32_bf16 v[14:17], v[156:159], v[212:215], v[14:17]
	v_mfma_f32_16x16x32_bf16 v[50:53], v[160:163], v[176:179], v[50:53]
	v_mfma_f32_16x16x32_bf16 v[42:45], v[168:171], v[176:179], v[42:45]
	v_mfma_f32_16x16x32_bf16 v[34:37], v[160:163], v[184:187], v[34:37]
	v_mfma_f32_16x16x32_bf16 v[26:29], v[168:171], v[184:187], v[26:29]
	v_mfma_f32_16x16x32_bf16 v[18:21], v[160:163], v[192:195], v[18:21]
	v_mfma_f32_16x16x32_bf16 v[10:13], v[168:171], v[192:195], v[10:13]
	v_mfma_f32_16x16x32_bf16 v[6:9], v[160:163], v[200:203], v[6:9]
	v_mfma_f32_16x16x32_bf16 v[2:5], v[168:171], v[200:203], v[2:5]
	v_mfma_f32_16x16x32_bf16 v[50:53], v[164:167], v[180:183], v[50:53]
	v_mfma_f32_16x16x32_bf16 v[42:45], v[172:175], v[180:183], v[42:45]
	v_mfma_f32_16x16x32_bf16 v[34:37], v[164:167], v[188:191], v[34:37]
	v_mfma_f32_16x16x32_bf16 v[26:29], v[172:175], v[188:191], v[26:29]
	v_mfma_f32_16x16x32_bf16 v[18:21], v[164:167], v[196:199], v[18:21]
	v_mfma_f32_16x16x32_bf16 v[10:13], v[172:175], v[196:199], v[10:13]
	v_mfma_f32_16x16x32_bf16 v[6:9], v[164:167], v[212:215], v[6:9]
	v_mfma_f32_16x16x32_bf16 v[2:5], v[172:175], v[212:215], v[2:5]
	s_setprio 0
	s_barrier
	s_add_i32 s70, s70, 2
	s_add_u32 s46, s46, 0x100
	s_addc_u32 s47, s47, 0
	s_add_u32 s68, s68, 0x100
	s_addc_u32 s69, s69, 0
	s_cmp_gt_u32 s70, 13
	s_cbranch_scc0 .LBB0_197
	s_and_b64 vcc, exec, s[26:27]
	s_cbranch_vccz .LBB0_200
	s_barrier

; #define PG8_STAGE(bufoff, gbase, voff) do { _Pragma("unroll") for (int _i = 0; _i < 2; ++_i) \
;         __builtin_amdgcn_global_load_lds((const unsigned*)((const char*)(gbase) + (voff)[_i]), (PG8_LAS unsigned*)(lds + (bufoff) + ldsw + _i * 8192), 16, 0, 0); } while (0)
; #define PG8_LDA(dst, b, h) do { _Pragma("unroll") for (int m = 0; m < 4; ++m) _Pragma("unroll") for (int k = 0; k < 2; ++k) dst[m][k] = *(const PG8_LAS bf16x8*)(lds + PG8_SA(b, h) + aoff + m * 2048 + k * 1024); } while (0)
; #define PG8_LDB(dst, b, h) do { _Pragma("unroll") for (int n = 0; n < 2; ++n) _Pragma("unroll") for (int k = 0; k < 2; ++k) dst[n][k] = *(const PG8_LAS bf16x8*)(lds + PG8_SB(b, h) + boff + n * 2048 + k * 1024); } while (0)
; #define PG8_MMA(ai, bj, At, Bt) do { __builtin_amdgcn_s_setprio(1); _Pragma("unroll") for (int m = 0; m < 4; ++m) _Pragma("unroll") for (int n = 0; n < 2; ++n) _Pragma("unroll") for (int k = 0; k < 2; ++k) \
;         acc[ai][bj][m][n] = __builtin_amdgcn_mfma_f32_16x16x32_bf16(Bt[n][k], At[m][k], acc[ai][bj][m][n], 0, 0, 0); __builtin_amdgcn_s_setprio(0); } while (0)
; #define PG8_WAIT_V(n) asm volatile("s_waitcnt vmcnt(" #n ")" ::: "memory")
; #define PG8_WAIT_L(n) asm volatile("s_waitcnt lgkmcnt(" #n ")" ::: "memory")
; template <class Epi, class Sched, bool ALIGN_EPI = false, bool SP2 = false>
; __device__ __forceinline__ void gemm_phase(PG8_LAS unsigned char* lds, const Gemm g, const Sched& S, const Epi& E) {
;     ...
;             const bool last = (t == unt - 2);
;             const char* a1 = cA + (size_t)(t + 1) * kstep;
;             const char* a2 = last ? nA : cA + (size_t)(t + 2) * kstep; const char* b2 = last ? nB : cB + (size_t)(t + 2) * kstep;
;             const char* a3 = a2 + kstep; const char* b3 = b2 + kstep;
;             if (last && has_next) S.a_ready(nxt);
;             if constexpr (SP2) {
;             PG8_LDB(B0, 0, 0); PG8_LDB(B1, 0, 1); PG8_SCHED; PG8_LDA(At, 0, 0); PG8_STAGE(PG8_SA(1, 1), a1 + hstep, voffA);
;             PG8_WAIT_V(8); PG8_WAIT_L(0); PG8_BAR; PG8_MMA(0, 0, At, B0); PG8_MMA(0, 1, At, B1); PG8_BAR; PG8_SCHED;
;             PG8_LDA(At, 0, 1); PG8_STAGE(PG8_SB(0, 0), b2, voffB); PG8_STAGE(PG8_SB(0, 1), b2 + hstep, voffB); PG8_STAGE(PG8_SA(0, 0), a2, voffA);
;             PG8_WAIT_V(8); PG8_WAIT_L(0); PG8_BAR; PG8_MMA(1, 0, At, B0); PG8_MMA(1, 1, At, B1); PG8_BAR; PG8_SCHED;
.LBB0_768:
	s_add_i32 s53, s51, 2
	s_add_u32 s40, s34, 0x100
	s_addc_u32 s41, s35, 0
	s_add_i32 s6, 0, 0x10000
	s_cmp_eq_u32 s5, s51
	s_cselect_b32 s63, s57, s41
	s_cselect_b32 s62, s56, s40
	s_cselect_b32 s61, s59, s27
	s_cselect_b32 s60, s58, s25
	s_add_i32 s51, 0, 0x14000
	s_waitcnt vmcnt(0)
	v_add_u32_e32 v78, s6, v163
	v_add_u32_e32 v160, s51, v163
	ds_read_b128 v[54:57], v78
	ds_read_b128 v[62:65], v78 offset:1024
	ds_read_b128 v[70:73], v78 offset:2048
	ds_read_b128 v[78:81], v78 offset:3072
	ds_read_b128 v[152:155], v160
	ds_read_b128 v[156:159], v160 offset:1024
	ds_read_b128 v[166:169], v160 offset:2048
	ds_read_b128 v[170:173], v160 offset:3072
	s_add_i32 m0, s45, 0xc000
	ds_read_b128 v[174:177], v165
	ds_read_b128 v[178:181], v165 offset:1024
	ds_read_b128 v[182:185], v165 offset:2048
	ds_read_b128 v[186:189], v165 offset:3072
	ds_read_b128 v[190:193], v165 offset:4096
	ds_read_b128 v[194:197], v165 offset:5120
	ds_read_b128 v[198:201], v165 offset:6144
	ds_read_b128 v[202:205], v165 offset:7168
	global_load_lds_dwordx4 v148, s[34:35]
	s_add_i32 m0, s45, 0xe000
	s_nop 0
	global_load_lds_dwordx4 v150, s[34:35]
	s_waitcnt vmcnt(8)
	s_waitcnt lgkmcnt(0)
	s_barrier
	s_setprio 1
	v_mfma_f32_16x16x32_bf16 v[142:145], v[54:57], v[174:177], v[142:145]
	v_mfma_f32_16x16x32_bf16 v[138:141], v[70:73], v[174:177], v[138:141]
	v_mfma_f32_16x16x32_bf16 v[126:129], v[54:57], v[182:185], v[126:129]
	v_mfma_f32_16x16x32_bf16 v[122:125], v[70:73], v[182:185], v[122:125]
	v_mfma_f32_16x16x32_bf16 v[110:113], v[54:57], v[190:193], v[110:113]
	v_mfma_f32_16x16x32_bf16 v[106:109], v[70:73], v[190:193], v[106:109]
	v_mfma_f32_16x16x32_bf16 v[94:97], v[54:57], v[198:201], v[94:97]
	v_mfma_f32_16x16x32_bf16 v[90:93], v[70:73], v[198:201], v[90:93]
	v_mfma_f32_16x16x32_bf16 v[142:145], v[62:65], v[178:181], v[142:145]
	v_mfma_f32_16x16x32_bf16 v[138:141], v[78:81], v[178:181], v[138:141]
	v_mfma_f32_16x16x32_bf16 v[126:129], v[62:65], v[186:189], v[126:129]
	v_mfma_f32_16x16x32_bf16 v[122:125], v[78:81], v[186:189], v[122:125]
	v_mfma_f32_16x16x32_bf16 v[110:113], v[62:65], v[194:197], v[110:113]
	v_mfma_f32_16x16x32_bf16 v[106:109], v[78:81], v[194:197], v[106:109]
	v_mfma_f32_16x16x32_bf16 v[94:97], v[62:65], v[202:205], v[94:97]
	v_mfma_f32_16x16x32_bf16 v[90:93], v[78:81], v[202:205], v[90:93]
	v_mfma_f32_16x16x32_bf16 v[134:137], v[152:155], v[174:177], v[134:137]
	v_mfma_f32_16x16x32_bf16 v[130:133], v[166:169], v[174:177], v[130:133]
	v_mfma_f32_16x16x32_bf16 v[118:121], v[152:155], v[182:185], v[118:121]
	v_mfma_f32_16x16x32_bf16 v[114:117], v[166:169], v[182:185], v[114:117]
	v_mfma_f32_16x16x32_bf16 v[102:105], v[152:155], v[190:193], v[102:105]
	v_mfma_f32_16x16x32_bf16 v[98:101], v[166:169], v[190:193], v[98:101]
	v_mfma_f32_16x16x32_bf16 v[86:89], v[152:155], v[198:201], v[86:89]
	v_mfma_f32_16x16x32_bf16 v[82:85], v[166:169], v[198:201], v[82:85]
	v_mfma_f32_16x16x32_bf16 v[134:137], v[156:159], v[178:181], v[134:137]
	v_mfma_f32_16x16x32_bf16 v[130:133], v[170:173], v[178:181], v[130:133]
	v_mfma_f32_16x16x32_bf16 v[118:121], v[156:159], v[186:189], v[118:121]
	v_mfma_f32_16x16x32_bf16 v[114:117], v[170:173], v[186:189], v[114:117]
	v_mfma_f32_16x16x32_bf16 v[102:105], v[156:159], v[194:197], v[102:105]
	v_mfma_f32_16x16x32_bf16 v[98:101], v[170:173], v[194:197], v[98:101]
	v_mfma_f32_16x16x32_bf16 v[86:89], v[156:159], v[202:205], v[86:89]
	v_mfma_f32_16x16x32_bf16 v[82:85], v[170:173], v[202:205], v[82:85]
	s_setprio 0
	s_barrier
	s_add_i32 s6, s6, s69
	s_add_u32 s98, s60, s22
	s_addc_u32 s99, s61, s23
	s_mov_b32 m0, s6
	ds_read_b128 v[174:177], v165 offset:16384
	ds_read_b128 v[178:181], v165 offset:17408
	ds_read_b128 v[182:185], v165 offset:18432
	ds_read_b128 v[186:189], v165 offset:19456
	ds_read_b128 v[190:193], v165 offset:20480
	ds_read_b128 v[194:197], v165 offset:21504
	ds_read_b128 v[198:201], v165 offset:22528
	ds_read_b128 v[202:205], v165 offset:23552
	global_load_lds_dwordx4 v0, s[60:61]
	s_add_i32 m0, s6, 0x2000
	s_add_u32 s6, s60, 0x40000
	s_addc_u32 s7, s61, 0
	s_add_i32 s34, s51, s69
	global_load_lds_dwordx4 v146, s[60:61]
	s_mov_b32 m0, s34
	s_add_u32 s100, s62, s22
	s_addc_u32 s101, s63, s23
	global_load_lds_dwordx4 v0, s[6:7]
	s_add_i32 m0, s34, 0x2000
	s_nop 0
	global_load_lds_dwordx4 v146, s[6:7]
	s_mov_b32 m0, s45
	s_nop 0
	global_load_lds_dwordx4 v0, s[62:63]
	s_mov_b32 m0, s82
	s_nop 0
	global_load_lds_dwordx4 v146, s[62:63]
	s_waitcnt vmcnt(8)
	s_waitcnt lgkmcnt(0)
	s_barrier
	s_setprio 1
	v_mfma_f32_16x16x32_bf16 v[74:77], v[54:57], v[174:177], v[74:77]
	v_mfma_f32_16x16x32_bf16 v[66:69], v[70:73], v[174:177], v[66:69]
	v_mfma_f32_16x16x32_bf16 v[46:49], v[54:57], v[182:185], v[46:49]
	v_mfma_f32_16x16x32_bf16 v[42:45], v[70:73], v[182:185], v[42:45]
	v_mfma_f32_16x16x32_bf16 v[30:33], v[54:57], v[190:193], v[30:33]
	v_mfma_f32_16x16x32_bf16 v[26:29], v[70:73], v[190:193], v[26:29]
	v_mfma_f32_16x16x32_bf16 v[14:17], v[54:57], v[198:201], v[14:17]
	v_mfma_f32_16x16x32_bf16 v[10:13], v[70:73], v[198:201], v[10:13]
	v_mfma_f32_16x16x32_bf16 v[74:77], v[62:65], v[178:181], v[74:77]
	v_mfma_f32_16x16x32_bf16 v[66:69], v[78:81], v[178:181], v[66:69]
	v_mfma_f32_16x16x32_bf16 v[46:49], v[62:65], v[186:189], v[46:49]
	v_mfma_f32_16x16x32_bf16 v[42:45], v[78:81], v[186:189], v[42:45]
	v_mfma_f32_16x16x32_bf16 v[30:33], v[62:65], v[194:197], v[30:33]
	v_mfma_f32_16x16x32_bf16 v[26:29], v[78:81], v[194:197], v[26:29]
	v_mfma_f32_16x16x32_bf16 v[14:17], v[62:65], v[202:205], v[14:17]
	v_mfma_f32_16x16x32_bf16 v[10:13], v[78:81], v[202:205], v[10:13]
	v_mfma_f32_16x16x32_bf16 v[50:53], v[166:169], v[174:177], v[50:53]
	v_mfma_f32_16x16x32_bf16 v[38:41], v[152:155], v[182:185], v[38:41]
	v_mfma_f32_16x16x32_bf16 v[34:37], v[166:169], v[182:185], v[34:37]
	v_mfma_f32_16x16x32_bf16 v[22:25], v[152:155], v[190:193], v[22:25]
	v_mfma_f32_16x16x32_bf16 v[18:21], v[166:169], v[190:193], v[18:21]
	v_mfma_f32_16x16x32_bf16 v[6:9], v[152:155], v[198:201], v[6:9]
	v_mfma_f32_16x16x32_bf16 v[2:5], v[166:169], v[198:201], v[2:5]
	v_mfma_f32_16x16x32_bf16 v[54:57], v[152:155], v[174:177], v[58:61]
	v_mfma_f32_16x16x32_bf16 v[50:53], v[170:173], v[178:181], v[50:53]
	v_mfma_f32_16x16x32_bf16 v[38:41], v[156:159], v[186:189], v[38:41]
	v_mfma_f32_16x16x32_bf16 v[34:37], v[170:173], v[186:189], v[34:37]
	v_mfma_f32_16x16x32_bf16 v[22:25], v[156:159], v[194:197], v[22:25]
	v_mfma_f32_16x16x32_bf16 v[18:21], v[170:173], v[194:197], v[18:21]
	v_mfma_f32_16x16x32_bf16 v[6:9], v[156:159], v[202:205], v[6:9]
	v_mfma_f32_16x16x32_bf16 v[2:5], v[170:173], v[202:205], v[2:5]
	v_mfma_f32_16x16x32_bf16 v[54:57], v[156:159], v[178:181], v[54:57]
	s_setprio 0
	s_barrier
; #define PG8_STAGE(bufoff, gbase, voff) do { _Pragma("unroll") for (int _i = 0; _i < 2; ++_i) \
;         __builtin_amdgcn_global_load_lds((const unsigned*)((const char*)(gbase) + (voff)[_i]), (PG8_LAS unsigned*)(lds + (bufoff) + ldsw + _i * 8192), 16, 0, 0); } while (0)
; #define PG8_LDA(dst, b, h) do { _Pragma("unroll") for (int m = 0; m < 4; ++m) _Pragma("unroll") for (int k = 0; k < 2; ++k) dst[m][k] = *(const PG8_LAS bf16x8*)(lds + PG8_SA(b, h) + aoff + m * 2048 + k * 1024); } while (0)
; #define PG8_LDB(dst, b, h) do { _Pragma("unroll") for (int n = 0; n < 2; ++n) _Pragma("unroll") for (int k = 0; k < 2; ++k) dst[n][k] = *(const PG8_LAS bf16x8*)(lds + PG8_SB(b, h) + boff + n * 2048 + k * 1024); } while (0)
; #define PG8_MMA(ai, bj, At, Bt) do { __builtin_amdgcn_s_setprio(1); _Pragma("unroll") for (int m = 0; m < 4; ++m) _Pragma("unroll") for (int n = 0; n < 2; ++n) _Pragma("unroll") for (int k = 0; k < 2; ++k) \
;         acc[ai][bj][m][n] = __builtin_amdgcn_mfma_f32_16x16x32_bf16(Bt[n][k], At[m][k], acc[ai][bj][m][n], 0, 0, 0); __builtin_amdgcn_s_setprio(0); } while (0)
; #define PG8_WAIT_V(n) asm volatile("s_waitcnt vmcnt(" #n ")" ::: "memory")
; #define PG8_WAIT_L(n) asm volatile("s_waitcnt lgkmcnt(" #n ")" ::: "memory")
; #define PG8_BAR __builtin_amdgcn_s_barrier()
; #define PG8_SCHED __builtin_amdgcn_sched_barrier(0)
; template <class Epi, class Sched, bool ALIGN_EPI = false, bool SP2 = false>
; __device__ __forceinline__ void gemm_phase(PG8_LAS unsigned char* lds, const Gemm g, const Sched& S, const Epi& E) {
;     ...
;             PG8_LDB(B0, 1, 0); PG8_LDB(B1, 1, 1); PG8_SCHED; PG8_LDA(At, 1, 0); PG8_STAGE(PG8_SA(0, 1), a2 + hstep, voffA);
;             PG8_WAIT_V(8); PG8_WAIT_L(0); PG8_BAR; PG8_MMA(0, 0, At, B0); PG8_MMA(0, 1, At, B1); PG8_BAR; PG8_SCHED;
;             PG8_LDA(At, 1, 1); PG8_STAGE(PG8_SB(1, 0), b3, voffB); PG8_STAGE(PG8_SB(1, 1), b3 + hstep, voffB); PG8_STAGE(PG8_SA(1, 0), a3, voffA);
;             PG8_WAIT_V(8); PG8_WAIT_L(0); PG8_BAR; PG8_MMA(1, 0, At, B0); PG8_MMA(1, 1, At, B1); PG8_BAR; PG8_SCHED;
;     ...
;         if constexpr (ALIGN_EPI) { if (wr == 0) PG8_BAR; }
	s_add_i32 s34, 0, 0x18000
	s_add_i32 s35, 0, 0x1c000
	v_add_u32_e32 v78, s34, v163
	v_add_u32_e32 v170, s35, v163
	ds_read_b128 v[58:61], v78
	ds_read_b128 v[62:65], v78 offset:1024
	ds_read_b128 v[70:73], v78 offset:2048
	ds_read_b128 v[78:81], v78 offset:3072
	ds_read_b128 v[152:155], v170
	ds_read_b128 v[156:159], v170 offset:1024
	ds_read_b128 v[166:169], v170 offset:2048
	ds_read_b128 v[170:173], v170 offset:3072
	s_add_u32 s6, s62, 0x40000
	s_addc_u32 s7, s63, 0
	s_mov_b32 m0, s83
	ds_read_b128 v[174:177], v165 offset:32768
	ds_read_b128 v[178:181], v165 offset:33792
	ds_read_b128 v[182:185], v165 offset:34816
	ds_read_b128 v[186:189], v165 offset:35840
	ds_read_b128 v[190:193], v165 offset:36864
	ds_read_b128 v[194:197], v165 offset:37888
	ds_read_b128 v[198:201], v165 offset:38912
	ds_read_b128 v[202:205], v165 offset:39936
	global_load_lds_dwordx4 v0, s[6:7]
	s_mov_b32 m0, s84
	s_nop 0
	global_load_lds_dwordx4 v146, s[6:7]
	s_waitcnt vmcnt(8)
	s_waitcnt lgkmcnt(0)
	s_barrier
	s_setprio 1
	v_mfma_f32_16x16x32_bf16 v[142:145], v[58:61], v[174:177], v[142:145]
	v_mfma_f32_16x16x32_bf16 v[138:141], v[70:73], v[174:177], v[138:141]
	v_mfma_f32_16x16x32_bf16 v[126:129], v[58:61], v[182:185], v[126:129]
	v_mfma_f32_16x16x32_bf16 v[122:125], v[70:73], v[182:185], v[122:125]
	v_mfma_f32_16x16x32_bf16 v[110:113], v[58:61], v[190:193], v[110:113]
	v_mfma_f32_16x16x32_bf16 v[106:109], v[70:73], v[190:193], v[106:109]
	v_mfma_f32_16x16x32_bf16 v[94:97], v[58:61], v[198:201], v[94:97]
	v_mfma_f32_16x16x32_bf16 v[90:93], v[70:73], v[198:201], v[90:93]
	v_mfma_f32_16x16x32_bf16 v[142:145], v[62:65], v[178:181], v[142:145]
	v_mfma_f32_16x16x32_bf16 v[138:141], v[78:81], v[178:181], v[138:141]
	v_mfma_f32_16x16x32_bf16 v[126:129], v[62:65], v[186:189], v[126:129]
	v_mfma_f32_16x16x32_bf16 v[122:125], v[78:81], v[186:189], v[122:125]
	v_mfma_f32_16x16x32_bf16 v[110:113], v[62:65], v[194:197], v[110:113]
	v_mfma_f32_16x16x32_bf16 v[106:109], v[78:81], v[194:197], v[106:109]
	v_mfma_f32_16x16x32_bf16 v[94:97], v[62:65], v[202:205], v[94:97]
	v_mfma_f32_16x16x32_bf16 v[90:93], v[78:81], v[202:205], v[90:93]
	v_mfma_f32_16x16x32_bf16 v[134:137], v[152:155], v[174:177], v[134:137]
	v_mfma_f32_16x16x32_bf16 v[130:133], v[166:169], v[174:177], v[130:133]
	v_mfma_f32_16x16x32_bf16 v[118:121], v[152:155], v[182:185], v[118:121]
	v_mfma_f32_16x16x32_bf16 v[114:117], v[166:169], v[182:185], v[114:117]
	v_mfma_f32_16x16x32_bf16 v[102:105], v[152:155], v[190:193], v[102:105]
	v_mfma_f32_16x16x32_bf16 v[98:101], v[166:169], v[190:193], v[98:101]
	v_mfma_f32_16x16x32_bf16 v[86:89], v[152:155], v[198:201], v[86:89]
	v_mfma_f32_16x16x32_bf16 v[82:85], v[166:169], v[198:201], v[82:85]
	v_mfma_f32_16x16x32_bf16 v[134:137], v[156:159], v[178:181], v[134:137]
	v_mfma_f32_16x16x32_bf16 v[130:133], v[170:173], v[178:181], v[130:133]
	v_mfma_f32_16x16x32_bf16 v[118:121], v[156:159], v[186:189], v[118:121]
	v_mfma_f32_16x16x32_bf16 v[114:117], v[170:173], v[186:189], v[114:117]
	v_mfma_f32_16x16x32_bf16 v[102:105], v[156:159], v[194:197], v[102:105]
	v_mfma_f32_16x16x32_bf16 v[98:101], v[170:173], v[194:197], v[98:101]
	v_mfma_f32_16x16x32_bf16 v[86:89], v[156:159], v[202:205], v[86:89]
	v_mfma_f32_16x16x32_bf16 v[82:85], v[170:173], v[202:205], v[82:85]
	s_setprio 0
	s_barrier
	s_add_i32 s6, s34, s69
	s_mov_b32 m0, s6
	ds_read_b128 v[174:177], v165 offset:49152
	ds_read_b128 v[178:181], v165 offset:50176
	ds_read_b128 v[182:185], v165 offset:51200
	ds_read_b128 v[186:189], v165 offset:52224
	ds_read_b128 v[190:193], v165 offset:53248
	ds_read_b128 v[194:197], v165 offset:54272
	ds_read_b128 v[198:201], v165 offset:55296
	ds_read_b128 v[202:205], v165 offset:56320
	global_load_lds_dwordx4 v0, s[98:99]
	s_add_i32 m0, s6, 0x2000
	s_add_u32 s6, s60, 0x40080
	s_addc_u32 s7, s61, 0
	s_add_i32 s34, s35, s69
	global_load_lds_dwordx4 v146, s[98:99]
	s_mov_b32 m0, s34
	s_nop 0
	global_load_lds_dwordx4 v0, s[6:7]
	s_add_i32 m0, s34, 0x2000
	s_nop 0
	global_load_lds_dwordx4 v146, s[6:7]
	s_mov_b32 m0, s93
	s_nop 0
	global_load_lds_dwordx4 v0, s[100:101]
	s_mov_b32 m0, s94
	s_nop 0
	global_load_lds_dwordx4 v146, s[100:101]
	s_waitcnt vmcnt(8)
	s_waitcnt lgkmcnt(0)
	s_barrier
	s_setprio 1
	v_mfma_f32_16x16x32_bf16 v[74:77], v[58:61], v[174:177], v[74:77]
	v_mfma_f32_16x16x32_bf16 v[66:69], v[70:73], v[174:177], v[66:69]
	v_mfma_f32_16x16x32_bf16 v[46:49], v[58:61], v[182:185], v[46:49]
	v_mfma_f32_16x16x32_bf16 v[42:45], v[70:73], v[182:185], v[42:45]
	v_mfma_f32_16x16x32_bf16 v[30:33], v[58:61], v[190:193], v[30:33]
	v_mfma_f32_16x16x32_bf16 v[26:29], v[70:73], v[190:193], v[26:29]
	v_mfma_f32_16x16x32_bf16 v[14:17], v[58:61], v[198:201], v[14:17]
	v_mfma_f32_16x16x32_bf16 v[10:13], v[70:73], v[198:201], v[10:13]
	v_mfma_f32_16x16x32_bf16 v[74:77], v[62:65], v[178:181], v[74:77]
	v_mfma_f32_16x16x32_bf16 v[66:69], v[78:81], v[178:181], v[66:69]
	v_mfma_f32_16x16x32_bf16 v[46:49], v[62:65], v[186:189], v[46:49]
	v_mfma_f32_16x16x32_bf16 v[42:45], v[78:81], v[186:189], v[42:45]
	v_mfma_f32_16x16x32_bf16 v[30:33], v[62:65], v[194:197], v[30:33]
	v_mfma_f32_16x16x32_bf16 v[26:29], v[78:81], v[194:197], v[26:29]
	v_mfma_f32_16x16x32_bf16 v[14:17], v[62:65], v[202:205], v[14:17]
	v_mfma_f32_16x16x32_bf16 v[10:13], v[78:81], v[202:205], v[10:13]
	v_mfma_f32_16x16x32_bf16 v[54:57], v[152:155], v[174:177], v[54:57]
	v_mfma_f32_16x16x32_bf16 v[50:53], v[166:169], v[174:177], v[50:53]
	v_mfma_f32_16x16x32_bf16 v[38:41], v[152:155], v[182:185], v[38:41]
	v_mfma_f32_16x16x32_bf16 v[34:37], v[166:169], v[182:185], v[34:37]
	v_mfma_f32_16x16x32_bf16 v[22:25], v[152:155], v[190:193], v[22:25]
	v_mfma_f32_16x16x32_bf16 v[18:21], v[166:169], v[190:193], v[18:21]
	v_mfma_f32_16x16x32_bf16 v[6:9], v[152:155], v[198:201], v[6:9]
	v_mfma_f32_16x16x32_bf16 v[2:5], v[166:169], v[198:201], v[2:5]
	v_mfma_f32_16x16x32_bf16 v[58:61], v[156:159], v[178:181], v[54:57]
	v_mfma_f32_16x16x32_bf16 v[50:53], v[170:173], v[178:181], v[50:53]
	v_mfma_f32_16x16x32_bf16 v[38:41], v[156:159], v[186:189], v[38:41]
	v_mfma_f32_16x16x32_bf16 v[34:37], v[170:173], v[186:189], v[34:37]
	v_mfma_f32_16x16x32_bf16 v[22:25], v[156:159], v[194:197], v[22:25]
	v_mfma_f32_16x16x32_bf16 v[18:21], v[170:173], v[194:197], v[18:21]
	v_mfma_f32_16x16x32_bf16 v[6:9], v[156:159], v[202:205], v[6:9]
	v_mfma_f32_16x16x32_bf16 v[2:5], v[170:173], v[202:205], v[2:5]
	s_setprio 0
	s_barrier
	s_add_u32 s25, s25, 0x100
	s_addc_u32 s27, s27, 0
	s_cmp_ge_i32 s53, s4
	s_mov_b64 s[34:35], s[40:41]
	s_mov_b32 s51, s53
	s_cbranch_scc0 .LBB0_768
	s_and_b64 vcc, exec, s[48:49]
	s_cbranch_vccz .LBB0_771

; #define PG8_STAGE(bufoff, gbase, voff) do { _Pragma("unroll") for (int _i = 0; _i < 2; ++_i) \
;         __builtin_amdgcn_global_load_lds((const unsigned*)((const char*)(gbase) + (voff)[_i]), (PG8_LAS unsigned*)(lds + (bufoff) + ldsw + _i * 8192), 16, 0, 0); } while (0)
; #define PG8_LDA(dst, b, h) do { _Pragma("unroll") for (int m = 0; m < 4; ++m) _Pragma("unroll") for (int k = 0; k < 2; ++k) dst[m][k] = *(const PG8_LAS bf16x8*)(lds + PG8_SA(b, h) + aoff + m * 2048 + k * 1024); } while (0)
; #define PG8_LDB(dst, b, h) do { _Pragma("unroll") for (int n = 0; n < 2; ++n) _Pragma("unroll") for (int k = 0; k < 2; ++k) dst[n][k] = *(const PG8_LAS bf16x8*)(lds + PG8_SB(b, h) + boff + n * 2048 + k * 1024); } while (0)
; #define PG8_MMA(ai, bj, At, Bt) do { __builtin_amdgcn_s_setprio(1); _Pragma("unroll") for (int m = 0; m < 4; ++m) _Pragma("unroll") for (int n = 0; n < 2; ++n) _Pragma("unroll") for (int k = 0; k < 2; ++k) \
;         acc[ai][bj][m][n] = __builtin_amdgcn_mfma_f32_16x16x32_bf16(Bt[n][k], At[m][k], acc[ai][bj][m][n], 0, 0, 0); __builtin_amdgcn_s_setprio(0); } while (0)
; #define PG8_WAIT_V(n) asm volatile("s_waitcnt vmcnt(" #n ")" ::: "memory")
; #define PG8_WAIT_L(n) asm volatile("s_waitcnt lgkmcnt(" #n ")" ::: "memory")
; template <class Epi, class Sched, bool ALIGN_EPI = false, bool SP2 = false>
; __device__ __forceinline__ void gemm_phase(PG8_LAS unsigned char* lds, const Gemm g, const Sched& S, const Epi& E) {
;     ...
;             const bool last = (t == unt - 2);
;             const char* a1 = cA + (size_t)(t + 1) * kstep;
;             const char* a2 = last ? nA : cA + (size_t)(t + 2) * kstep; const char* b2 = last ? nB : cB + (size_t)(t + 2) * kstep;
;             const char* a3 = a2 + kstep; const char* b3 = b2 + kstep;
;             if (last && has_next) S.a_ready(nxt);
;             if constexpr (SP2) {
;             PG8_LDB(B0, 0, 0); PG8_LDB(B1, 0, 1); PG8_SCHED; PG8_LDA(At, 0, 0); PG8_STAGE(PG8_SA(1, 1), a1 + hstep, voffA);
;             PG8_WAIT_V(8); PG8_WAIT_L(0); PG8_BAR; PG8_MMA(0, 0, At, B0); PG8_MMA(0, 1, At, B1); PG8_BAR; PG8_SCHED;
;             PG8_LDA(At, 0, 1); PG8_STAGE(PG8_SB(0, 0), b2, voffB); PG8_STAGE(PG8_SB(0, 1), b2 + hstep, voffB); PG8_STAGE(PG8_SA(0, 0), a2, voffA);
;             PG8_WAIT_V(8); PG8_WAIT_L(0); PG8_BAR; PG8_MMA(1, 0, At, B0); PG8_MMA(1, 1, At, B1); PG8_BAR; PG8_SCHED;
.LBB0_1026:
	s_add_u32 s6, s46, 0xfffc0080
	s_addc_u32 s7, s47, -1
	s_add_i32 s76, 0, 0x10000
	s_cmp_eq_u32 s71, 12
	s_cselect_b32 s51, s5, s7
	s_cselect_b32 s50, s35, s6
	v_add_u32_e32 v140, s76, v143
	s_cselect_b32 s49, s31, s70
	s_cselect_b32 s48, s68, s69
	s_add_i32 s77, 0, 0x14000
	ds_read_b128 v[146:149], v140
	ds_read_b128 v[150:153], v140 offset:1024
	ds_read_b128 v[154:157], v140 offset:2048
	ds_read_b128 v[158:161], v140 offset:3072
	v_add_u32_e32 v140, s77, v143
	ds_read_b128 v[162:165], v140
	ds_read_b128 v[166:169], v140 offset:1024
	ds_read_b128 v[170:173], v140 offset:2048
	ds_read_b128 v[174:177], v140 offset:3072
	s_add_i32 m0, s45, 0xc000
	ds_read_b128 v[178:181], v145
	ds_read_b128 v[182:185], v145 offset:1024
	ds_read_b128 v[186:189], v145 offset:2048
	ds_read_b128 v[190:193], v145 offset:3072
	ds_read_b128 v[194:197], v145 offset:4096
	ds_read_b128 v[198:201], v145 offset:5120
	ds_read_b128 v[202:205], v145 offset:6144
	ds_read_b128 v[212:215], v145 offset:7168
	global_load_lds_dwordx4 v136, s[46:47]
	s_add_i32 m0, s45, 0xe000
	s_nop 0
	global_load_lds_dwordx4 v138, s[46:47]
	s_waitcnt vmcnt(8)
	s_waitcnt lgkmcnt(0)
	s_barrier
	s_setprio 1
	v_mfma_f32_16x16x32_bf16 v[126:129], v[146:149], v[178:181], v[126:129]
	v_mfma_f32_16x16x32_bf16 v[122:125], v[154:157], v[178:181], v[122:125]
	v_mfma_f32_16x16x32_bf16 v[110:113], v[146:149], v[186:189], v[110:113]
	v_mfma_f32_16x16x32_bf16 v[106:109], v[154:157], v[186:189], v[106:109]
	v_mfma_f32_16x16x32_bf16 v[94:97], v[146:149], v[194:197], v[94:97]
	v_mfma_f32_16x16x32_bf16 v[90:93], v[154:157], v[194:197], v[90:93]
	v_mfma_f32_16x16x32_bf16 v[78:81], v[146:149], v[202:205], v[78:81]
	v_mfma_f32_16x16x32_bf16 v[74:77], v[154:157], v[202:205], v[74:77]
	v_mfma_f32_16x16x32_bf16 v[126:129], v[150:153], v[182:185], v[126:129]
	v_mfma_f32_16x16x32_bf16 v[122:125], v[158:161], v[182:185], v[122:125]
	v_mfma_f32_16x16x32_bf16 v[110:113], v[150:153], v[190:193], v[110:113]
	v_mfma_f32_16x16x32_bf16 v[106:109], v[158:161], v[190:193], v[106:109]
	v_mfma_f32_16x16x32_bf16 v[94:97], v[150:153], v[198:201], v[94:97]
	v_mfma_f32_16x16x32_bf16 v[90:93], v[158:161], v[198:201], v[90:93]
	v_mfma_f32_16x16x32_bf16 v[78:81], v[150:153], v[212:215], v[78:81]
	v_mfma_f32_16x16x32_bf16 v[74:77], v[158:161], v[212:215], v[74:77]
	v_mfma_f32_16x16x32_bf16 v[118:121], v[162:165], v[178:181], v[118:121]
	v_mfma_f32_16x16x32_bf16 v[114:117], v[170:173], v[178:181], v[114:117]
	v_mfma_f32_16x16x32_bf16 v[102:105], v[162:165], v[186:189], v[102:105]
	v_mfma_f32_16x16x32_bf16 v[98:101], v[170:173], v[186:189], v[98:101]
	v_mfma_f32_16x16x32_bf16 v[86:89], v[162:165], v[194:197], v[86:89]
	v_mfma_f32_16x16x32_bf16 v[82:85], v[170:173], v[194:197], v[82:85]
	v_mfma_f32_16x16x32_bf16 v[70:73], v[162:165], v[202:205], v[70:73]
	v_mfma_f32_16x16x32_bf16 v[66:69], v[170:173], v[202:205], v[66:69]
	v_mfma_f32_16x16x32_bf16 v[118:121], v[166:169], v[182:185], v[118:121]
	v_mfma_f32_16x16x32_bf16 v[114:117], v[174:177], v[182:185], v[114:117]
	v_mfma_f32_16x16x32_bf16 v[102:105], v[166:169], v[190:193], v[102:105]
	v_mfma_f32_16x16x32_bf16 v[98:101], v[174:177], v[190:193], v[98:101]
	v_mfma_f32_16x16x32_bf16 v[86:89], v[166:169], v[198:201], v[86:89]
	v_mfma_f32_16x16x32_bf16 v[82:85], v[174:177], v[198:201], v[82:85]
	v_mfma_f32_16x16x32_bf16 v[70:73], v[166:169], v[212:215], v[70:73]
	v_mfma_f32_16x16x32_bf16 v[66:69], v[174:177], v[212:215], v[66:69]
	s_setprio 0
	s_barrier
	s_add_i32 s6, s76, s60
	s_add_u32 s98, s48, s22
	s_addc_u32 s99, s49, s23
	s_mov_b32 m0, s6
	ds_read_b128 v[178:181], v145 offset:16384
	ds_read_b128 v[182:185], v145 offset:17408
	ds_read_b128 v[186:189], v145 offset:18432
	ds_read_b128 v[190:193], v145 offset:19456
	ds_read_b128 v[194:197], v145 offset:20480
	ds_read_b128 v[198:201], v145 offset:21504
	ds_read_b128 v[202:205], v145 offset:22528
	ds_read_b128 v[212:215], v145 offset:23552
	global_load_lds_dwordx4 v0, s[48:49]
	s_add_i32 m0, s6, 0x2000
	s_add_u32 s6, s48, 0x40000
	s_addc_u32 s7, s49, 0
	s_add_i32 s76, s77, s60
	global_load_lds_dwordx4 v130, s[48:49]
	s_mov_b32 m0, s76
	s_add_u32 s100, s50, s22
	s_addc_u32 s101, s51, s23
	global_load_lds_dwordx4 v0, s[6:7]
	s_add_i32 m0, s76, 0x2000
	s_nop 0
	global_load_lds_dwordx4 v130, s[6:7]
	s_mov_b32 m0, s45
	s_nop 0
	global_load_lds_dwordx4 v134, s[50:51]
	s_mov_b32 m0, s62
	s_nop 0
	global_load_lds_dwordx4 v132, s[50:51]
	s_waitcnt vmcnt(8)
	s_waitcnt lgkmcnt(0)
	s_barrier
	s_setprio 1
	v_mfma_f32_16x16x32_bf16 v[62:65], v[146:149], v[178:181], v[62:65]
	v_mfma_f32_16x16x32_bf16 v[58:61], v[154:157], v[178:181], v[58:61]
	v_mfma_f32_16x16x32_bf16 v[46:49], v[146:149], v[186:189], v[46:49]
	v_mfma_f32_16x16x32_bf16 v[42:45], v[154:157], v[186:189], v[42:45]
	v_mfma_f32_16x16x32_bf16 v[30:33], v[146:149], v[194:197], v[30:33]
	v_mfma_f32_16x16x32_bf16 v[26:29], v[154:157], v[194:197], v[26:29]
	v_mfma_f32_16x16x32_bf16 v[14:17], v[146:149], v[202:205], v[14:17]
	v_mfma_f32_16x16x32_bf16 v[10:13], v[154:157], v[202:205], v[10:13]
	v_mfma_f32_16x16x32_bf16 v[62:65], v[150:153], v[182:185], v[62:65]
	v_mfma_f32_16x16x32_bf16 v[58:61], v[158:161], v[182:185], v[58:61]
	v_mfma_f32_16x16x32_bf16 v[46:49], v[150:153], v[190:193], v[46:49]
	v_mfma_f32_16x16x32_bf16 v[42:45], v[158:161], v[190:193], v[42:45]
	v_mfma_f32_16x16x32_bf16 v[30:33], v[150:153], v[198:201], v[30:33]
	v_mfma_f32_16x16x32_bf16 v[26:29], v[158:161], v[198:201], v[26:29]
	v_mfma_f32_16x16x32_bf16 v[14:17], v[150:153], v[212:215], v[14:17]
	v_mfma_f32_16x16x32_bf16 v[10:13], v[158:161], v[212:215], v[10:13]
	v_mfma_f32_16x16x32_bf16 v[54:57], v[162:165], v[178:181], v[54:57]
	v_mfma_f32_16x16x32_bf16 v[50:53], v[170:173], v[178:181], v[50:53]
	v_mfma_f32_16x16x32_bf16 v[38:41], v[162:165], v[186:189], v[38:41]
	v_mfma_f32_16x16x32_bf16 v[34:37], v[170:173], v[186:189], v[34:37]
	v_mfma_f32_16x16x32_bf16 v[22:25], v[162:165], v[194:197], v[22:25]
	v_mfma_f32_16x16x32_bf16 v[18:21], v[170:173], v[194:197], v[18:21]
	v_mfma_f32_16x16x32_bf16 v[6:9], v[162:165], v[202:205], v[6:9]
	v_mfma_f32_16x16x32_bf16 v[2:5], v[170:173], v[202:205], v[2:5]
	v_mfma_f32_16x16x32_bf16 v[54:57], v[166:169], v[182:185], v[54:57]
	v_mfma_f32_16x16x32_bf16 v[50:53], v[174:177], v[182:185], v[50:53]
	v_mfma_f32_16x16x32_bf16 v[38:41], v[166:169], v[190:193], v[38:41]
	v_mfma_f32_16x16x32_bf16 v[34:37], v[174:177], v[190:193], v[34:37]
	v_mfma_f32_16x16x32_bf16 v[22:25], v[166:169], v[198:201], v[22:25]
	v_mfma_f32_16x16x32_bf16 v[18:21], v[174:177], v[198:201], v[18:21]
	v_mfma_f32_16x16x32_bf16 v[6:9], v[166:169], v[212:215], v[6:9]
	v_mfma_f32_16x16x32_bf16 v[2:5], v[174:177], v[212:215], v[2:5]
	s_setprio 0
	s_barrier
; #define PG8_STAGE(bufoff, gbase, voff) do { _Pragma("unroll") for (int _i = 0; _i < 2; ++_i) \
;         __builtin_amdgcn_global_load_lds((const unsigned*)((const char*)(gbase) + (voff)[_i]), (PG8_LAS unsigned*)(lds + (bufoff) + ldsw + _i * 8192), 16, 0, 0); } while (0)
; #define PG8_LDA(dst, b, h) do { _Pragma("unroll") for (int m = 0; m < 4; ++m) _Pragma("unroll") for (int k = 0; k < 2; ++k) dst[m][k] = *(const PG8_LAS bf16x8*)(lds + PG8_SA(b, h) + aoff + m * 2048 + k * 1024); } while (0)
; #define PG8_LDB(dst, b, h) do { _Pragma("unroll") for (int n = 0; n < 2; ++n) _Pragma("unroll") for (int k = 0; k < 2; ++k) dst[n][k] = *(const PG8_LAS bf16x8*)(lds + PG8_SB(b, h) + boff + n * 2048 + k * 1024); } while (0)
; #define PG8_MMA(ai, bj, At, Bt) do { __builtin_amdgcn_s_setprio(1); _Pragma("unroll") for (int m = 0; m < 4; ++m) _Pragma("unroll") for (int n = 0; n < 2; ++n) _Pragma("unroll") for (int k = 0; k < 2; ++k) \
;         acc[ai][bj][m][n] = __builtin_amdgcn_mfma_f32_16x16x32_bf16(Bt[n][k], At[m][k], acc[ai][bj][m][n], 0, 0, 0); __builtin_amdgcn_s_setprio(0); } while (0)
; #define PG8_WAIT_V(n) asm volatile("s_waitcnt vmcnt(" #n ")" ::: "memory")
; #define PG8_WAIT_L(n) asm volatile("s_waitcnt lgkmcnt(" #n ")" ::: "memory")
; #define PG8_BAR __builtin_amdgcn_s_barrier()
; #define PG8_SCHED __builtin_amdgcn_sched_barrier(0)
; template <class Epi, class Sched, bool ALIGN_EPI = false, bool SP2 = false>
; __device__ __forceinline__ void gemm_phase(PG8_LAS unsigned char* lds, const Gemm g, const Sched& S, const Epi& E) {
;     ...
;             PG8_LDB(B0, 1, 0); PG8_LDB(B1, 1, 1); PG8_SCHED; PG8_LDA(At, 1, 0); PG8_STAGE(PG8_SA(0, 1), a2 + hstep, voffA);
;             PG8_WAIT_V(8); PG8_WAIT_L(0); PG8_BAR; PG8_MMA(0, 0, At, B0); PG8_MMA(0, 1, At, B1); PG8_BAR; PG8_SCHED;
;             PG8_LDA(At, 1, 1); PG8_STAGE(PG8_SB(1, 0), b3, voffB); PG8_STAGE(PG8_SB(1, 1), b3 + hstep, voffB); PG8_STAGE(PG8_SA(1, 0), a3, voffA);
;             PG8_WAIT_V(8); PG8_WAIT_L(0); PG8_BAR; PG8_MMA(1, 0, At, B0); PG8_MMA(1, 1, At, B1); PG8_BAR; PG8_SCHED;
;     ...
;         if constexpr (ALIGN_EPI) { if (wr == 0) PG8_BAR; }
	s_add_i32 s76, 0, 0x18000
	s_add_i32 s77, 0, 0x1c000
	v_add_u32_e32 v158, s76, v143
	v_add_u32_e32 v174, s77, v143
	ds_read_b128 v[146:149], v158
	ds_read_b128 v[150:153], v158 offset:1024
	ds_read_b128 v[154:157], v158 offset:2048
	ds_read_b128 v[158:161], v158 offset:3072
	ds_read_b128 v[162:165], v174
	ds_read_b128 v[166:169], v174 offset:1024
	ds_read_b128 v[170:173], v174 offset:2048
	ds_read_b128 v[174:177], v174 offset:3072
	s_add_u32 s6, s50, 0x40000
	s_addc_u32 s7, s51, 0
	s_mov_b32 m0, s63
	ds_read_b128 v[178:181], v145 offset:32768
	ds_read_b128 v[182:185], v145 offset:33792
	ds_read_b128 v[186:189], v145 offset:34816
	ds_read_b128 v[190:193], v145 offset:35840
	ds_read_b128 v[194:197], v145 offset:36864
	ds_read_b128 v[198:201], v145 offset:37888
	ds_read_b128 v[202:205], v145 offset:38912
	ds_read_b128 v[212:215], v145 offset:39936
	global_load_lds_dwordx4 v134, s[6:7]
	s_mov_b32 m0, s64
	s_nop 0
	global_load_lds_dwordx4 v132, s[6:7]
	s_waitcnt vmcnt(8)
	s_waitcnt lgkmcnt(0)
	s_barrier
	s_setprio 1
	v_mfma_f32_16x16x32_bf16 v[126:129], v[146:149], v[178:181], v[126:129]
	v_mfma_f32_16x16x32_bf16 v[122:125], v[154:157], v[178:181], v[122:125]
	v_mfma_f32_16x16x32_bf16 v[110:113], v[146:149], v[186:189], v[110:113]
	v_mfma_f32_16x16x32_bf16 v[106:109], v[154:157], v[186:189], v[106:109]
	v_mfma_f32_16x16x32_bf16 v[94:97], v[146:149], v[194:197], v[94:97]
	v_mfma_f32_16x16x32_bf16 v[90:93], v[154:157], v[194:197], v[90:93]
	v_mfma_f32_16x16x32_bf16 v[78:81], v[146:149], v[202:205], v[78:81]
	v_mfma_f32_16x16x32_bf16 v[74:77], v[154:157], v[202:205], v[74:77]
	v_mfma_f32_16x16x32_bf16 v[126:129], v[150:153], v[182:185], v[126:129]
	v_mfma_f32_16x16x32_bf16 v[122:125], v[158:161], v[182:185], v[122:125]
	v_mfma_f32_16x16x32_bf16 v[110:113], v[150:153], v[190:193], v[110:113]
	v_mfma_f32_16x16x32_bf16 v[106:109], v[158:161], v[190:193], v[106:109]
	v_mfma_f32_16x16x32_bf16 v[94:97], v[150:153], v[198:201], v[94:97]
	v_mfma_f32_16x16x32_bf16 v[90:93], v[158:161], v[198:201], v[90:93]
	v_mfma_f32_16x16x32_bf16 v[78:81], v[150:153], v[212:215], v[78:81]
	v_mfma_f32_16x16x32_bf16 v[74:77], v[158:161], v[212:215], v[74:77]
	v_mfma_f32_16x16x32_bf16 v[118:121], v[162:165], v[178:181], v[118:121]
	v_mfma_f32_16x16x32_bf16 v[114:117], v[170:173], v[178:181], v[114:117]
	v_mfma_f32_16x16x32_bf16 v[102:105], v[162:165], v[186:189], v[102:105]
	v_mfma_f32_16x16x32_bf16 v[98:101], v[170:173], v[186:189], v[98:101]
	v_mfma_f32_16x16x32_bf16 v[86:89], v[162:165], v[194:197], v[86:89]
	v_mfma_f32_16x16x32_bf16 v[82:85], v[170:173], v[194:197], v[82:85]
	v_mfma_f32_16x16x32_bf16 v[70:73], v[162:165], v[202:205], v[70:73]
	v_mfma_f32_16x16x32_bf16 v[66:69], v[170:173], v[202:205], v[66:69]
	v_mfma_f32_16x16x32_bf16 v[118:121], v[166:169], v[182:185], v[118:121]
	v_mfma_f32_16x16x32_bf16 v[114:117], v[174:177], v[182:185], v[114:117]
	v_mfma_f32_16x16x32_bf16 v[102:105], v[166:169], v[190:193], v[102:105]
	v_mfma_f32_16x16x32_bf16 v[98:101], v[174:177], v[190:193], v[98:101]
	v_mfma_f32_16x16x32_bf16 v[86:89], v[166:169], v[198:201], v[86:89]
	v_mfma_f32_16x16x32_bf16 v[82:85], v[174:177], v[198:201], v[82:85]
	v_mfma_f32_16x16x32_bf16 v[70:73], v[166:169], v[212:215], v[70:73]
	v_mfma_f32_16x16x32_bf16 v[66:69], v[174:177], v[212:215], v[66:69]
	s_setprio 0
	s_barrier
	s_add_i32 s6, s76, s60
	s_mov_b32 m0, s6
	ds_read_b128 v[178:181], v145 offset:49152
	ds_read_b128 v[182:185], v145 offset:50176
	ds_read_b128 v[186:189], v145 offset:51200
	ds_read_b128 v[190:193], v145 offset:52224
	ds_read_b128 v[194:197], v145 offset:53248
	ds_read_b128 v[198:201], v145 offset:54272
	ds_read_b128 v[202:205], v145 offset:55296
	ds_read_b128 v[212:215], v145 offset:56320
	global_load_lds_dwordx4 v0, s[98:99]
	s_add_i32 m0, s6, 0x2000
	s_add_u32 s6, s48, 0x40080
	s_addc_u32 s7, s49, 0
	s_add_i32 s48, s77, s60
	global_load_lds_dwordx4 v130, s[98:99]
	s_mov_b32 m0, s48
	s_nop 0
	global_load_lds_dwordx4 v0, s[6:7]
	s_add_i32 m0, s48, 0x2000
	s_nop 0
	global_load_lds_dwordx4 v130, s[6:7]
	s_mov_b32 m0, s65
	s_nop 0
	global_load_lds_dwordx4 v134, s[100:101]
	s_mov_b32 m0, s66
	s_nop 0
	global_load_lds_dwordx4 v132, s[100:101]
	s_waitcnt vmcnt(8)
	s_waitcnt lgkmcnt(0)
	s_barrier
	s_setprio 1
	v_mfma_f32_16x16x32_bf16 v[62:65], v[146:149], v[178:181], v[62:65]
	v_mfma_f32_16x16x32_bf16 v[58:61], v[154:157], v[178:181], v[58:61]
	v_mfma_f32_16x16x32_bf16 v[46:49], v[146:149], v[186:189], v[46:49]
	v_mfma_f32_16x16x32_bf16 v[42:45], v[154:157], v[186:189], v[42:45]
	v_mfma_f32_16x16x32_bf16 v[30:33], v[146:149], v[194:197], v[30:33]
	v_mfma_f32_16x16x32_bf16 v[26:29], v[154:157], v[194:197], v[26:29]
	v_mfma_f32_16x16x32_bf16 v[14:17], v[146:149], v[202:205], v[14:17]
	v_mfma_f32_16x16x32_bf16 v[10:13], v[154:157], v[202:205], v[10:13]
	v_mfma_f32_16x16x32_bf16 v[62:65], v[150:153], v[182:185], v[62:65]
	v_mfma_f32_16x16x32_bf16 v[58:61], v[158:161], v[182:185], v[58:61]
	v_mfma_f32_16x16x32_bf16 v[46:49], v[150:153], v[190:193], v[46:49]
	v_mfma_f32_16x16x32_bf16 v[42:45], v[158:161], v[190:193], v[42:45]
	v_mfma_f32_16x16x32_bf16 v[30:33], v[150:153], v[198:201], v[30:33]
	v_mfma_f32_16x16x32_bf16 v[26:29], v[158:161], v[198:201], v[26:29]
	v_mfma_f32_16x16x32_bf16 v[14:17], v[150:153], v[212:215], v[14:17]
	v_mfma_f32_16x16x32_bf16 v[10:13], v[158:161], v[212:215], v[10:13]
	v_mfma_f32_16x16x32_bf16 v[54:57], v[162:165], v[178:181], v[54:57]
	v_mfma_f32_16x16x32_bf16 v[50:53], v[170:173], v[178:181], v[50:53]
	v_mfma_f32_16x16x32_bf16 v[38:41], v[162:165], v[186:189], v[38:41]
	v_mfma_f32_16x16x32_bf16 v[34:37], v[170:173], v[186:189], v[34:37]
	v_mfma_f32_16x16x32_bf16 v[22:25], v[162:165], v[194:197], v[22:25]
	v_mfma_f32_16x16x32_bf16 v[18:21], v[170:173], v[194:197], v[18:21]
	v_mfma_f32_16x16x32_bf16 v[6:9], v[162:165], v[202:205], v[6:9]
	v_mfma_f32_16x16x32_bf16 v[2:5], v[170:173], v[202:205], v[2:5]
	v_mfma_f32_16x16x32_bf16 v[54:57], v[166:169], v[182:185], v[54:57]
	v_mfma_f32_16x16x32_bf16 v[50:53], v[174:177], v[182:185], v[50:53]
	v_mfma_f32_16x16x32_bf16 v[38:41], v[166:169], v[190:193], v[38:41]
	v_mfma_f32_16x16x32_bf16 v[34:37], v[174:177], v[190:193], v[34:37]
	v_mfma_f32_16x16x32_bf16 v[22:25], v[166:169], v[198:201], v[22:25]
	v_mfma_f32_16x16x32_bf16 v[18:21], v[174:177], v[198:201], v[18:21]
	v_mfma_f32_16x16x32_bf16 v[6:9], v[166:169], v[212:215], v[6:9]
	v_mfma_f32_16x16x32_bf16 v[2:5], v[174:177], v[212:215], v[2:5]
	s_setprio 0
	s_barrier
	s_add_i32 s71, s71, 2
	s_add_u32 s46, s46, 0x100
	s_addc_u32 s47, s47, 0
	s_add_u32 s69, s69, 0x100
	s_addc_u32 s70, s70, 0
	s_cmp_gt_u32 s71, 13
	s_cbranch_scc0 .LBB0_1026
	s_and_b64 vcc, exec, s[26:27]
	s_cbranch_vccz .LBB0_1029
	s_barrier

; #define PG8_STAGE(bufoff, gbase, voff) do { _Pragma("unroll") for (int _i = 0; _i < 2; ++_i) \
;         __builtin_amdgcn_global_load_lds((const unsigned*)((const char*)(gbase) + (voff)[_i]), (PG8_LAS unsigned*)(lds + (bufoff) + ldsw + _i * 8192), 16, 0, 0); } while (0)
; #define PG8_LDA(dst, b, h) do { _Pragma("unroll") for (int m = 0; m < 4; ++m) _Pragma("unroll") for (int k = 0; k < 2; ++k) dst[m][k] = *(const PG8_LAS bf16x8*)(lds + PG8_SA(b, h) + aoff + m * 2048 + k * 1024); } while (0)
; #define PG8_LDB(dst, b, h) do { _Pragma("unroll") for (int n = 0; n < 2; ++n) _Pragma("unroll") for (int k = 0; k < 2; ++k) dst[n][k] = *(const PG8_LAS bf16x8*)(lds + PG8_SB(b, h) + boff + n * 2048 + k * 1024); } while (0)
; #define PG8_MMA(ai, bj, At, Bt) do { __builtin_amdgcn_s_setprio(1); _Pragma("unroll") for (int m = 0; m < 4; ++m) _Pragma("unroll") for (int n = 0; n < 2; ++n) _Pragma("unroll") for (int k = 0; k < 2; ++k) \
;         acc[ai][bj][m][n] = __builtin_amdgcn_mfma_f32_16x16x32_bf16(Bt[n][k], At[m][k], acc[ai][bj][m][n], 0, 0, 0); __builtin_amdgcn_s_setprio(0); } while (0)
; #define PG8_WAIT_V(n) asm volatile("s_waitcnt vmcnt(" #n ")" ::: "memory")
; #define PG8_WAIT_L(n) asm volatile("s_waitcnt lgkmcnt(" #n ")" ::: "memory")
; template <class Epi, class Sched, bool ALIGN_EPI = false, bool SP2 = false>
; __device__ __forceinline__ void gemm_phase(PG8_LAS unsigned char* lds, const Gemm g, const Sched& S, const Epi& E) {
;     ...
;             const bool last = (t == unt - 2);
;             const char* a1 = cA + (size_t)(t + 1) * kstep;
;             const char* a2 = last ? nA : cA + (size_t)(t + 2) * kstep; const char* b2 = last ? nB : cB + (size_t)(t + 2) * kstep;
;             const char* a3 = a2 + kstep; const char* b3 = b2 + kstep;
;             if (last && has_next) S.a_ready(nxt);
;             if constexpr (SP2) {
;             PG8_LDB(B0, 0, 0); PG8_LDB(B1, 0, 1); PG8_SCHED; PG8_LDA(At, 0, 0); PG8_STAGE(PG8_SA(1, 1), a1 + hstep, voffA);
;             PG8_WAIT_V(8); PG8_WAIT_L(0); PG8_BAR; PG8_MMA(0, 0, At, B0); PG8_MMA(0, 1, At, B1); PG8_BAR; PG8_SCHED;
;             PG8_LDA(At, 0, 1); PG8_STAGE(PG8_SB(0, 0), b2, voffB); PG8_STAGE(PG8_SB(0, 1), b2 + hstep, voffB); PG8_STAGE(PG8_SA(0, 0), a2, voffA);
;             PG8_WAIT_V(8); PG8_WAIT_L(0); PG8_BAR; PG8_MMA(1, 0, At, B0); PG8_MMA(1, 1, At, B1); PG8_BAR; PG8_SCHED;
.LBB0_1122:
	s_add_i32 s51, s49, 2
	s_add_u32 s40, s34, 0x100
	s_addc_u32 s41, s35, 0
	s_add_i32 s6, 0, 0x10000
	s_cmp_eq_u32 s5, s49
	s_cselect_b32 s61, s55, s41
	s_cselect_b32 s60, s54, s40
	s_cselect_b32 s59, s57, s27
	s_cselect_b32 s58, s56, s25
	s_add_i32 s49, 0, 0x14000
	s_waitcnt vmcnt(0)
	v_add_u32_e32 v78, s6, v163
	v_add_u32_e32 v160, s49, v163
	ds_read_b128 v[54:57], v78
	ds_read_b128 v[62:65], v78 offset:1024
	ds_read_b128 v[70:73], v78 offset:2048
	ds_read_b128 v[78:81], v78 offset:3072
	ds_read_b128 v[152:155], v160
	ds_read_b128 v[156:159], v160 offset:1024
	ds_read_b128 v[166:169], v160 offset:2048
	ds_read_b128 v[170:173], v160 offset:3072
	s_add_i32 m0, s43, 0xc000
	ds_read_b128 v[174:177], v165
	ds_read_b128 v[178:181], v165 offset:1024
	ds_read_b128 v[182:185], v165 offset:2048
	ds_read_b128 v[186:189], v165 offset:3072
	ds_read_b128 v[190:193], v165 offset:4096
	ds_read_b128 v[194:197], v165 offset:5120
	ds_read_b128 v[198:201], v165 offset:6144
	ds_read_b128 v[202:205], v165 offset:7168
	global_load_lds_dwordx4 v148, s[34:35]
	s_add_i32 m0, s43, 0xe000
	s_nop 0
	global_load_lds_dwordx4 v150, s[34:35]
	s_waitcnt vmcnt(8)
	s_waitcnt lgkmcnt(0)
	s_barrier
	s_setprio 1
	v_mfma_f32_16x16x32_bf16 v[142:145], v[54:57], v[174:177], v[142:145]
	v_mfma_f32_16x16x32_bf16 v[138:141], v[70:73], v[174:177], v[138:141]
	v_mfma_f32_16x16x32_bf16 v[126:129], v[54:57], v[182:185], v[126:129]
	v_mfma_f32_16x16x32_bf16 v[122:125], v[70:73], v[182:185], v[122:125]
	v_mfma_f32_16x16x32_bf16 v[110:113], v[54:57], v[190:193], v[110:113]
	v_mfma_f32_16x16x32_bf16 v[106:109], v[70:73], v[190:193], v[106:109]
	v_mfma_f32_16x16x32_bf16 v[94:97], v[54:57], v[198:201], v[94:97]
	v_mfma_f32_16x16x32_bf16 v[90:93], v[70:73], v[198:201], v[90:93]
	v_mfma_f32_16x16x32_bf16 v[142:145], v[62:65], v[178:181], v[142:145]
	v_mfma_f32_16x16x32_bf16 v[138:141], v[78:81], v[178:181], v[138:141]
	v_mfma_f32_16x16x32_bf16 v[126:129], v[62:65], v[186:189], v[126:129]
	v_mfma_f32_16x16x32_bf16 v[122:125], v[78:81], v[186:189], v[122:125]
	v_mfma_f32_16x16x32_bf16 v[110:113], v[62:65], v[194:197], v[110:113]
	v_mfma_f32_16x16x32_bf16 v[106:109], v[78:81], v[194:197], v[106:109]
	v_mfma_f32_16x16x32_bf16 v[94:97], v[62:65], v[202:205], v[94:97]
	v_mfma_f32_16x16x32_bf16 v[90:93], v[78:81], v[202:205], v[90:93]
	v_mfma_f32_16x16x32_bf16 v[134:137], v[152:155], v[174:177], v[134:137]
	v_mfma_f32_16x16x32_bf16 v[130:133], v[166:169], v[174:177], v[130:133]
	v_mfma_f32_16x16x32_bf16 v[118:121], v[152:155], v[182:185], v[118:121]
	v_mfma_f32_16x16x32_bf16 v[114:117], v[166:169], v[182:185], v[114:117]
	v_mfma_f32_16x16x32_bf16 v[102:105], v[152:155], v[190:193], v[102:105]
	v_mfma_f32_16x16x32_bf16 v[98:101], v[166:169], v[190:193], v[98:101]
	v_mfma_f32_16x16x32_bf16 v[86:89], v[152:155], v[198:201], v[86:89]
	v_mfma_f32_16x16x32_bf16 v[82:85], v[166:169], v[198:201], v[82:85]
	v_mfma_f32_16x16x32_bf16 v[134:137], v[156:159], v[178:181], v[134:137]
	v_mfma_f32_16x16x32_bf16 v[130:133], v[170:173], v[178:181], v[130:133]
	v_mfma_f32_16x16x32_bf16 v[118:121], v[156:159], v[186:189], v[118:121]
	v_mfma_f32_16x16x32_bf16 v[114:117], v[170:173], v[186:189], v[114:117]
	v_mfma_f32_16x16x32_bf16 v[102:105], v[156:159], v[194:197], v[102:105]
	v_mfma_f32_16x16x32_bf16 v[98:101], v[170:173], v[194:197], v[98:101]
	v_mfma_f32_16x16x32_bf16 v[86:89], v[156:159], v[202:205], v[86:89]
	v_mfma_f32_16x16x32_bf16 v[82:85], v[170:173], v[202:205], v[82:85]
	s_setprio 0
	s_barrier
	s_add_i32 s6, s6, s67
	s_add_u32 s98, s58, s22
	s_addc_u32 s99, s59, s23
	s_mov_b32 m0, s6
	ds_read_b128 v[174:177], v165 offset:16384
	ds_read_b128 v[178:181], v165 offset:17408
	ds_read_b128 v[182:185], v165 offset:18432
	ds_read_b128 v[186:189], v165 offset:19456
	ds_read_b128 v[190:193], v165 offset:20480
	ds_read_b128 v[194:197], v165 offset:21504
	ds_read_b128 v[198:201], v165 offset:22528
	ds_read_b128 v[202:205], v165 offset:23552
	global_load_lds_dwordx4 v0, s[58:59]
	s_add_i32 m0, s6, 0x2000
	s_add_u32 s6, s58, 0x100000
	s_addc_u32 s7, s59, 0
	s_add_i32 s34, s49, s67
	global_load_lds_dwordx4 v146, s[58:59]
	s_mov_b32 m0, s34
	s_add_u32 s100, s60, s22
	s_addc_u32 s101, s61, s23
	global_load_lds_dwordx4 v0, s[6:7]
	s_add_i32 m0, s34, 0x2000
	s_nop 0
	global_load_lds_dwordx4 v146, s[6:7]
	s_mov_b32 m0, s43
	s_nop 0
	global_load_lds_dwordx4 v0, s[60:61]
	s_mov_b32 m0, s76
	s_nop 0
	global_load_lds_dwordx4 v146, s[60:61]
	s_waitcnt vmcnt(8)
	s_waitcnt lgkmcnt(0)
	s_barrier
	s_setprio 1
	v_mfma_f32_16x16x32_bf16 v[74:77], v[54:57], v[174:177], v[74:77]
	v_mfma_f32_16x16x32_bf16 v[66:69], v[70:73], v[174:177], v[66:69]
	v_mfma_f32_16x16x32_bf16 v[46:49], v[54:57], v[182:185], v[46:49]
	v_mfma_f32_16x16x32_bf16 v[42:45], v[70:73], v[182:185], v[42:45]
	v_mfma_f32_16x16x32_bf16 v[30:33], v[54:57], v[190:193], v[30:33]
	v_mfma_f32_16x16x32_bf16 v[26:29], v[70:73], v[190:193], v[26:29]
	v_mfma_f32_16x16x32_bf16 v[14:17], v[54:57], v[198:201], v[14:17]
	v_mfma_f32_16x16x32_bf16 v[10:13], v[70:73], v[198:201], v[10:13]
	v_mfma_f32_16x16x32_bf16 v[74:77], v[62:65], v[178:181], v[74:77]
	v_mfma_f32_16x16x32_bf16 v[66:69], v[78:81], v[178:181], v[66:69]
	v_mfma_f32_16x16x32_bf16 v[46:49], v[62:65], v[186:189], v[46:49]
	v_mfma_f32_16x16x32_bf16 v[42:45], v[78:81], v[186:189], v[42:45]
	v_mfma_f32_16x16x32_bf16 v[30:33], v[62:65], v[194:197], v[30:33]
	v_mfma_f32_16x16x32_bf16 v[26:29], v[78:81], v[194:197], v[26:29]
	v_mfma_f32_16x16x32_bf16 v[14:17], v[62:65], v[202:205], v[14:17]
	v_mfma_f32_16x16x32_bf16 v[10:13], v[78:81], v[202:205], v[10:13]
	v_mfma_f32_16x16x32_bf16 v[50:53], v[166:169], v[174:177], v[50:53]
	v_mfma_f32_16x16x32_bf16 v[38:41], v[152:155], v[182:185], v[38:41]
	v_mfma_f32_16x16x32_bf16 v[34:37], v[166:169], v[182:185], v[34:37]
	v_mfma_f32_16x16x32_bf16 v[22:25], v[152:155], v[190:193], v[22:25]
	v_mfma_f32_16x16x32_bf16 v[18:21], v[166:169], v[190:193], v[18:21]
	v_mfma_f32_16x16x32_bf16 v[6:9], v[152:155], v[198:201], v[6:9]
	v_mfma_f32_16x16x32_bf16 v[2:5], v[166:169], v[198:201], v[2:5]
	v_mfma_f32_16x16x32_bf16 v[54:57], v[152:155], v[174:177], v[58:61]
	v_mfma_f32_16x16x32_bf16 v[50:53], v[170:173], v[178:181], v[50:53]
	v_mfma_f32_16x16x32_bf16 v[38:41], v[156:159], v[186:189], v[38:41]
	v_mfma_f32_16x16x32_bf16 v[34:37], v[170:173], v[186:189], v[34:37]
	v_mfma_f32_16x16x32_bf16 v[22:25], v[156:159], v[194:197], v[22:25]
	v_mfma_f32_16x16x32_bf16 v[18:21], v[170:173], v[194:197], v[18:21]
	v_mfma_f32_16x16x32_bf16 v[6:9], v[156:159], v[202:205], v[6:9]
	v_mfma_f32_16x16x32_bf16 v[2:5], v[170:173], v[202:205], v[2:5]
	v_mfma_f32_16x16x32_bf16 v[54:57], v[156:159], v[178:181], v[54:57]
	s_setprio 0
	s_barrier
; #define PG8_STAGE(bufoff, gbase, voff) do { _Pragma("unroll") for (int _i = 0; _i < 2; ++_i) \
;         __builtin_amdgcn_global_load_lds((const unsigned*)((const char*)(gbase) + (voff)[_i]), (PG8_LAS unsigned*)(lds + (bufoff) + ldsw + _i * 8192), 16, 0, 0); } while (0)
; #define PG8_LDA(dst, b, h) do { _Pragma("unroll") for (int m = 0; m < 4; ++m) _Pragma("unroll") for (int k = 0; k < 2; ++k) dst[m][k] = *(const PG8_LAS bf16x8*)(lds + PG8_SA(b, h) + aoff + m * 2048 + k * 1024); } while (0)
; #define PG8_LDB(dst, b, h) do { _Pragma("unroll") for (int n = 0; n < 2; ++n) _Pragma("unroll") for (int k = 0; k < 2; ++k) dst[n][k] = *(const PG8_LAS bf16x8*)(lds + PG8_SB(b, h) + boff + n * 2048 + k * 1024); } while (0)
; #define PG8_MMA(ai, bj, At, Bt) do { __builtin_amdgcn_s_setprio(1); _Pragma("unroll") for (int m = 0; m < 4; ++m) _Pragma("unroll") for (int n = 0; n < 2; ++n) _Pragma("unroll") for (int k = 0; k < 2; ++k) \
;         acc[ai][bj][m][n] = __builtin_amdgcn_mfma_f32_16x16x32_bf16(Bt[n][k], At[m][k], acc[ai][bj][m][n], 0, 0, 0); __builtin_amdgcn_s_setprio(0); } while (0)
; #define PG8_WAIT_V(n) asm volatile("s_waitcnt vmcnt(" #n ")" ::: "memory")
; #define PG8_WAIT_L(n) asm volatile("s_waitcnt lgkmcnt(" #n ")" ::: "memory")
; #define PG8_BAR __builtin_amdgcn_s_barrier()
; #define PG8_SCHED __builtin_amdgcn_sched_barrier(0)
; template <class Epi, class Sched, bool ALIGN_EPI = false, bool SP2 = false>
; __device__ __forceinline__ void gemm_phase(PG8_LAS unsigned char* lds, const Gemm g, const Sched& S, const Epi& E) {
;     ...
;             PG8_LDB(B0, 1, 0); PG8_LDB(B1, 1, 1); PG8_SCHED; PG8_LDA(At, 1, 0); PG8_STAGE(PG8_SA(0, 1), a2 + hstep, voffA);
;             PG8_WAIT_V(8); PG8_WAIT_L(0); PG8_BAR; PG8_MMA(0, 0, At, B0); PG8_MMA(0, 1, At, B1); PG8_BAR; PG8_SCHED;
;             PG8_LDA(At, 1, 1); PG8_STAGE(PG8_SB(1, 0), b3, voffB); PG8_STAGE(PG8_SB(1, 1), b3 + hstep, voffB); PG8_STAGE(PG8_SA(1, 0), a3, voffA);
;             PG8_WAIT_V(8); PG8_WAIT_L(0); PG8_BAR; PG8_MMA(1, 0, At, B0); PG8_MMA(1, 1, At, B1); PG8_BAR; PG8_SCHED;
;     ...
;         if constexpr (ALIGN_EPI) { if (wr == 0) PG8_BAR; }
	s_add_i32 s34, 0, 0x18000
	s_add_i32 s35, 0, 0x1c000
	v_add_u32_e32 v78, s34, v163
	v_add_u32_e32 v170, s35, v163
	ds_read_b128 v[58:61], v78
	ds_read_b128 v[62:65], v78 offset:1024
	ds_read_b128 v[70:73], v78 offset:2048
	ds_read_b128 v[78:81], v78 offset:3072
	ds_read_b128 v[152:155], v170
	ds_read_b128 v[156:159], v170 offset:1024
	ds_read_b128 v[166:169], v170 offset:2048
	ds_read_b128 v[170:173], v170 offset:3072
	s_add_u32 s6, s60, 0x100000
	s_addc_u32 s7, s61, 0
	s_mov_b32 m0, s77
	ds_read_b128 v[174:177], v165 offset:32768
	ds_read_b128 v[178:181], v165 offset:33792
	ds_read_b128 v[182:185], v165 offset:34816
	ds_read_b128 v[186:189], v165 offset:35840
	ds_read_b128 v[190:193], v165 offset:36864
	ds_read_b128 v[194:197], v165 offset:37888
	ds_read_b128 v[198:201], v165 offset:38912
	ds_read_b128 v[202:205], v165 offset:39936
	global_load_lds_dwordx4 v0, s[6:7]
	s_mov_b32 m0, s82
	s_nop 0
	global_load_lds_dwordx4 v146, s[6:7]
	s_waitcnt vmcnt(8)
	s_waitcnt lgkmcnt(0)
	s_barrier
	s_setprio 1
	v_mfma_f32_16x16x32_bf16 v[142:145], v[58:61], v[174:177], v[142:145]
	v_mfma_f32_16x16x32_bf16 v[138:141], v[70:73], v[174:177], v[138:141]
	v_mfma_f32_16x16x32_bf16 v[126:129], v[58:61], v[182:185], v[126:129]
	v_mfma_f32_16x16x32_bf16 v[122:125], v[70:73], v[182:185], v[122:125]
	v_mfma_f32_16x16x32_bf16 v[110:113], v[58:61], v[190:193], v[110:113]
	v_mfma_f32_16x16x32_bf16 v[106:109], v[70:73], v[190:193], v[106:109]
	v_mfma_f32_16x16x32_bf16 v[94:97], v[58:61], v[198:201], v[94:97]
	v_mfma_f32_16x16x32_bf16 v[90:93], v[70:73], v[198:201], v[90:93]
	v_mfma_f32_16x16x32_bf16 v[142:145], v[62:65], v[178:181], v[142:145]
	v_mfma_f32_16x16x32_bf16 v[138:141], v[78:81], v[178:181], v[138:141]
	v_mfma_f32_16x16x32_bf16 v[126:129], v[62:65], v[186:189], v[126:129]
	v_mfma_f32_16x16x32_bf16 v[122:125], v[78:81], v[186:189], v[122:125]
	v_mfma_f32_16x16x32_bf16 v[110:113], v[62:65], v[194:197], v[110:113]
	v_mfma_f32_16x16x32_bf16 v[106:109], v[78:81], v[194:197], v[106:109]
	v_mfma_f32_16x16x32_bf16 v[94:97], v[62:65], v[202:205], v[94:97]
	v_mfma_f32_16x16x32_bf16 v[90:93], v[78:81], v[202:205], v[90:93]
	v_mfma_f32_16x16x32_bf16 v[134:137], v[152:155], v[174:177], v[134:137]
	v_mfma_f32_16x16x32_bf16 v[130:133], v[166:169], v[174:177], v[130:133]
	v_mfma_f32_16x16x32_bf16 v[118:121], v[152:155], v[182:185], v[118:121]
	v_mfma_f32_16x16x32_bf16 v[114:117], v[166:169], v[182:185], v[114:117]
	v_mfma_f32_16x16x32_bf16 v[102:105], v[152:155], v[190:193], v[102:105]
	v_mfma_f32_16x16x32_bf16 v[98:101], v[166:169], v[190:193], v[98:101]
	v_mfma_f32_16x16x32_bf16 v[86:89], v[152:155], v[198:201], v[86:89]
	v_mfma_f32_16x16x32_bf16 v[82:85], v[166:169], v[198:201], v[82:85]
	v_mfma_f32_16x16x32_bf16 v[134:137], v[156:159], v[178:181], v[134:137]
	v_mfma_f32_16x16x32_bf16 v[130:133], v[170:173], v[178:181], v[130:133]
	v_mfma_f32_16x16x32_bf16 v[118:121], v[156:159], v[186:189], v[118:121]
	v_mfma_f32_16x16x32_bf16 v[114:117], v[170:173], v[186:189], v[114:117]
	v_mfma_f32_16x16x32_bf16 v[102:105], v[156:159], v[194:197], v[102:105]
	v_mfma_f32_16x16x32_bf16 v[98:101], v[170:173], v[194:197], v[98:101]
	v_mfma_f32_16x16x32_bf16 v[86:89], v[156:159], v[202:205], v[86:89]
	v_mfma_f32_16x16x32_bf16 v[82:85], v[170:173], v[202:205], v[82:85]
	s_setprio 0
	s_barrier
	s_add_i32 s6, s34, s67
	s_mov_b32 m0, s6
	ds_read_b128 v[174:177], v165 offset:49152
	ds_read_b128 v[178:181], v165 offset:50176
	ds_read_b128 v[182:185], v165 offset:51200
	ds_read_b128 v[186:189], v165 offset:52224
	ds_read_b128 v[190:193], v165 offset:53248
	ds_read_b128 v[194:197], v165 offset:54272
	ds_read_b128 v[198:201], v165 offset:55296
	ds_read_b128 v[202:205], v165 offset:56320
	global_load_lds_dwordx4 v0, s[98:99]
	s_add_i32 m0, s6, 0x2000
	s_add_u32 s6, s58, 0x100080
	s_addc_u32 s7, s59, 0
	s_add_i32 s34, s35, s67
	global_load_lds_dwordx4 v146, s[98:99]
	s_mov_b32 m0, s34
	s_nop 0
	global_load_lds_dwordx4 v0, s[6:7]
	s_add_i32 m0, s34, 0x2000
	s_nop 0
	global_load_lds_dwordx4 v146, s[6:7]
	s_mov_b32 m0, s87
	s_nop 0
	global_load_lds_dwordx4 v0, s[100:101]
	s_mov_b32 m0, s92
	s_nop 0
	global_load_lds_dwordx4 v146, s[100:101]
	s_waitcnt vmcnt(8)
	s_waitcnt lgkmcnt(0)
	s_barrier
	s_setprio 1
	v_mfma_f32_16x16x32_bf16 v[74:77], v[58:61], v[174:177], v[74:77]
	v_mfma_f32_16x16x32_bf16 v[66:69], v[70:73], v[174:177], v[66:69]
	v_mfma_f32_16x16x32_bf16 v[46:49], v[58:61], v[182:185], v[46:49]
	v_mfma_f32_16x16x32_bf16 v[42:45], v[70:73], v[182:185], v[42:45]
	v_mfma_f32_16x16x32_bf16 v[30:33], v[58:61], v[190:193], v[30:33]
	v_mfma_f32_16x16x32_bf16 v[26:29], v[70:73], v[190:193], v[26:29]
	v_mfma_f32_16x16x32_bf16 v[14:17], v[58:61], v[198:201], v[14:17]
	v_mfma_f32_16x16x32_bf16 v[10:13], v[70:73], v[198:201], v[10:13]
	v_mfma_f32_16x16x32_bf16 v[74:77], v[62:65], v[178:181], v[74:77]
	v_mfma_f32_16x16x32_bf16 v[66:69], v[78:81], v[178:181], v[66:69]
	v_mfma_f32_16x16x32_bf16 v[46:49], v[62:65], v[186:189], v[46:49]
	v_mfma_f32_16x16x32_bf16 v[42:45], v[78:81], v[186:189], v[42:45]
	v_mfma_f32_16x16x32_bf16 v[30:33], v[62:65], v[194:197], v[30:33]
	v_mfma_f32_16x16x32_bf16 v[26:29], v[78:81], v[194:197], v[26:29]
	v_mfma_f32_16x16x32_bf16 v[14:17], v[62:65], v[202:205], v[14:17]
	v_mfma_f32_16x16x32_bf16 v[10:13], v[78:81], v[202:205], v[10:13]
	v_mfma_f32_16x16x32_bf16 v[54:57], v[152:155], v[174:177], v[54:57]
	v_mfma_f32_16x16x32_bf16 v[50:53], v[166:169], v[174:177], v[50:53]
	v_mfma_f32_16x16x32_bf16 v[38:41], v[152:155], v[182:185], v[38:41]
	v_mfma_f32_16x16x32_bf16 v[34:37], v[166:169], v[182:185], v[34:37]
	v_mfma_f32_16x16x32_bf16 v[22:25], v[152:155], v[190:193], v[22:25]
	v_mfma_f32_16x16x32_bf16 v[18:21], v[166:169], v[190:193], v[18:21]
	v_mfma_f32_16x16x32_bf16 v[6:9], v[152:155], v[198:201], v[6:9]
	v_mfma_f32_16x16x32_bf16 v[2:5], v[166:169], v[198:201], v[2:5]
	v_mfma_f32_16x16x32_bf16 v[58:61], v[156:159], v[178:181], v[54:57]
	v_mfma_f32_16x16x32_bf16 v[50:53], v[170:173], v[178:181], v[50:53]
	v_mfma_f32_16x16x32_bf16 v[38:41], v[156:159], v[186:189], v[38:41]
	v_mfma_f32_16x16x32_bf16 v[34:37], v[170:173], v[186:189], v[34:37]
	v_mfma_f32_16x16x32_bf16 v[22:25], v[156:159], v[194:197], v[22:25]
	v_mfma_f32_16x16x32_bf16 v[18:21], v[170:173], v[194:197], v[18:21]
	v_mfma_f32_16x16x32_bf16 v[6:9], v[156:159], v[202:205], v[6:9]
	v_mfma_f32_16x16x32_bf16 v[2:5], v[170:173], v[202:205], v[2:5]
	s_setprio 0
	s_barrier
	s_add_u32 s25, s25, 0x100
	s_addc_u32 s27, s27, 0
	s_cmp_ge_i32 s51, s4
	s_mov_b64 s[34:35], s[40:41]
	s_mov_b32 s49, s51
	s_cbranch_scc0 .LBB0_1122
	s_and_b64 vcc, exec, s[46:47]
	s_cbranch_vccz .LBB0_1125
